# job queue: mixer jobs request their next ticket before the final gated stores; dequeue waits only for that atomic
# baseline (speedup 1.0000x reference)
.LBB0_369:
	s_or_b64 exec, exec, s[0:1]
	v_readlane_b32 s8, v252, 2
	v_readlane_b32 s9, v252, 3
	s_mov_b64 s[8:9], 0x3e38aa3b
	v_readlane_b32 s10, v252, 4
	v_readlane_b32 s11, v252, 5
	v_readlane_b32 s14, v252, 8
	v_readlane_b32 s15, v252, 9
	s_lshl_b32 s0, s34, 4
	s_mov_b32 s1, s9
	s_mov_b64 s[14:15], s[10:11]
	s_lshl_b64 s[0:1], s[0:1], 2
	s_waitcnt lgkmcnt(0)
	s_barrier
	s_add_u32 s0, s14, s0
	s_addc_u32 s1, s15, s1
	s_add_u32 s0, s0, 0xf213640
	s_addc_u32 s1, s1, 0
	s_mov_b32 s10, s34
	v_writelane_b32 v253, s0, 49
	s_mov_b32 s11, s9
	v_readlane_b32 s12, v252, 6
	v_writelane_b32 v253, s1, 50
	s_lshl_b64 s[0:1], s[10:11], 2
	s_add_u32 s2, s14, s0
	s_addc_u32 s3, s15, s1
	s_add_u32 s0, s2, 0xf2136c0
	s_addc_u32 s1, s3, 0
	v_writelane_b32 v253, s0, 51
	v_readlane_b32 s13, v252, 7
	v_mov_b32_e32 v234, v250
	v_writelane_b32 v253, s1, 52
	s_nop 0
	v_readlane_b32 s0, v253, 25
	v_readlane_b32 s1, v253, 26
	s_and_b64 s[0:1], s[0:1], exec
	s_cselect_b32 s1, 0x80, 0
	s_cselect_b32 s0, 0xffffff80, 0
	s_or_b32 s8, s1, 0xc00
	v_writelane_b32 v253, s8, 53
	s_or_b32 s8, s1, 0x400
	v_writelane_b32 v253, s8, 54
	s_or_b32 s8, s1, 0x600
	v_writelane_b32 v253, s8, 55
	s_add_i32 s8, s0, 0xfffffa00
	v_writelane_b32 v253, s8, 56
	s_addk_i32 s0, 0xfc00
	v_writelane_b32 v253, s0, 57
	s_lshl_b32 s8, s34, 1
	s_lshl_b32 s79, s1, 8
	v_writelane_b32 v253, s8, 58
	s_lshl_b32 s8, s34, 11
	s_add_u32 s2, s2, 0xf213600
	s_addc_u32 s3, s3, 0
	v_writelane_b32 v253, s2, 59
	s_mul_i32 s0, s34, 0x18000
	s_mov_b32 s1, s9
	v_writelane_b32 v253, s3, 60
	s_add_u32 s2, s14, 0xb1d0000
	s_addc_u32 s3, s15, 0
	v_writelane_b32 v253, s2, 61
	s_nop 1
	v_writelane_b32 v253, s3, 62
	s_add_u32 s2, s14, 0xc9d0000
	s_addc_u32 s3, s15, 0
	v_writelane_b32 v253, s2, 63
	s_nop 1
	v_writelane_b32 v254, s3, 0
	s_add_u32 s2, s14, 0xbdd0000
	s_addc_u32 s3, s15, 0
	v_writelane_b32 v254, s2, 1
	s_nop 1
	v_writelane_b32 v254, s3, 2
	s_add_u32 s2, s14, 0x3dd0000
	s_addc_u32 s3, s15, 0
	v_writelane_b32 v254, s2, 3
	s_nop 1
	v_writelane_b32 v254, s3, 4
	s_add_u32 s2, s14, 0xd1d0000
	v_writelane_b32 v254, s2, 5
	s_addc_u32 s2, s15, 0
	v_writelane_b32 v254, s2, 6
	s_add_u32 s2, s14, 0xd1f0000
	v_writelane_b32 v254, s2, 7
	s_addc_u32 s2, s15, 0
	v_writelane_b32 v254, s2, 8
	s_add_u32 s2, s14, 0xd210000
	s_addc_u32 s3, s15, 0
	v_writelane_b32 v254, s2, 9
	s_nop 1
	v_writelane_b32 v254, s3, 10
	s_add_u32 s2, s14, 0xf00000
	v_writelane_b32 v254, s2, 11
	s_addc_u32 s2, s15, 0
	s_add_u32 s94, s14, 0x780000
	s_addc_u32 s95, s15, 0
	v_writelane_b32 v254, s2, 12
	s_add_u32 s2, s14, 0x1330000
	s_addc_u32 s3, s15, 0
	v_writelane_b32 v254, s2, 13
	s_nop 1
	v_writelane_b32 v254, s3, 14
	s_add_u32 s2, s14, 0x1380000
	s_addc_u32 s3, s15, 0
	s_add_u32 s20, s14, 0x15a0000
	s_addc_u32 s21, s15, 0
	s_add_u32 s96, s14, 0x16a0000
	v_writelane_b32 v254, s2, 15
	s_addc_u32 s97, s15, 0
	s_nop 0
	v_writelane_b32 v254, s3, 16
	s_add_u32 s2, s14, 0x17b0000
	s_addc_u32 s3, s15, 0
	v_writelane_b32 v254, s2, 17
	s_nop 1
	v_writelane_b32 v254, s3, 18
	s_add_u32 s2, s14, 0x17b8000
	s_addc_u32 s3, s15, 0
	v_writelane_b32 v254, s2, 19
	s_add_u32 s12, s14, 0x1bc0000
	s_addc_u32 s13, s15, 0
	v_writelane_b32 v254, s3, 20
	v_writelane_b32 v254, s12, 21
	s_nop 1
	v_writelane_b32 v254, s13, 22
	s_add_u32 s12, s14, 0x1cc0000
	s_addc_u32 s13, s15, 0
	v_writelane_b32 v254, s12, 23
	s_nop 1
	v_writelane_b32 v254, s13, 24
	s_add_u32 s12, s14, 0x3dd0a00
	s_addc_u32 s13, s15, 0
	s_lshl_b32 s10, s34, 17
	v_writelane_b32 v254, s12, 25
	s_add_u32 s10, s14, s10
	s_addc_u32 s11, s15, 0
	v_writelane_b32 v254, s13, 26
	s_mov_b32 s12, s34
	v_writelane_b32 v254, s12, 27
	s_add_u32 s10, s10, 0x1360000
	s_addc_u32 s11, s11, 0
	v_writelane_b32 v254, s13, 28
	v_writelane_b32 v254, s10, 29
	s_nop 1
	v_writelane_b32 v254, s11, 30
	s_add_u32 s10, s14, 0x3dd0800
	s_addc_u32 s11, s15, 0
	s_lshl_b64 s[0:1], s[0:1], 1
	s_add_u32 s0, s14, s0
	s_addc_u32 s1, s15, s1
	v_writelane_b32 v254, s10, 31
	s_add_u32 s0, s0, 0x1300000
	s_addc_u32 s1, s1, 0
	v_writelane_b32 v254, s11, 32
	v_writelane_b32 v254, s0, 33
	s_nop 1
	v_writelane_b32 v254, s1, 34
	s_add_u32 s0, s14, 0x13a0000
	v_writelane_b32 v254, s0, 35
	s_addc_u32 s0, s15, 0
	v_writelane_b32 v254, s0, 36
	s_mov_b64 s[0:1], 0
	v_writelane_b32 v254, s0, 37
	s_nop 1
	v_writelane_b32 v254, s1, 38
	s_lshl_b64 s[0:1], s[8:9], 2
	v_writelane_b32 v254, s0, 39
	s_nop 1
	v_writelane_b32 v254, s1, 40
	s_mov_b64 s[0:1], 0
	v_writelane_b32 v254, s0, 41
	s_nop 1
	v_writelane_b32 v254, s1, 42
	v_writelane_b32 v254, s14, 43
	s_nop 1
	v_writelane_b32 v254, s15, 44
	v_writelane_b32 v255, s0, 41
	s_branch .LBB0_374

.LBB0_374:
	v_mov_b32_e32 v198, v234
	s_nop 0
	v_cmp_eq_u32_e64 s[0:1], 0, v198
	s_and_saveexec_b64 s[8:9], s[0:1]
	s_cbranch_execz .Ljq_issued
	v_readlane_b32 s10, v255, 41
	s_cmp_lg_u32 s10, 0
	s_cbranch_scc1 .Ljq_issued
	v_readlane_b32 s10, v253, 59
	v_readlane_b32 s11, v253, 60
	s_nop 1
	v_mov_b64_e32 v[0:1], s[10:11]
	global_atomic_add v0, v[0:1], v251, off sc0
.Ljq_issued:
	s_or_b64 exec, exec, s[8:9]
	s_barrier
	s_and_saveexec_b64 s[8:9], s[0:1]
	s_cbranch_execz .LBB0_376
	v_readlane_b32 s10, v255, 41
	s_cmp_lg_u32 s10, 0
	s_cbranch_scc1 .Ljq_pend
	s_waitcnt vmcnt(0) lgkmcnt(0)
	s_branch .Ljq_got
.Ljq_pend:
	s_waitcnt vmcnt(3) lgkmcnt(0)
	v_readlane_b32 s10, v255, 40
	v_writelane_b32 v255, 0, 41
	v_mov_b32_e32 v0, s10
.Ljq_got:
	ds_write_b32 v222, v0

.LBB0_411:
	v_mbcnt_lo_u32_b32 v0, -1, 0
	v_mbcnt_hi_u32_b32 v0, -1, v0
	v_and_b32_e32 v2, 64, v0
	v_xor_b32_e32 v1, 32, v0
	v_add_u32_e32 v2, 64, v2
	v_cmp_lt_i32_e32 vcc, v1, v2
	s_movk_i32 s8, 0x1d00
	v_mov_b32_e32 v141, v193
	v_cndmask_b32_e32 v0, v0, v1, vcc
	v_lshlrev_b32_e32 v0, 2, v0
	ds_bpermute_b32 v0, v0, v163
	s_waitcnt lgkmcnt(0)
	v_add_f32_e32 v0, v163, v0
	v_div_scale_f32 v1, s[0:1], v0, v0, 1.0
	v_rcp_f32_e32 v2, v1
	v_readlane_b32 s0, v254, 43
	v_readlane_b32 s1, v254, 44
	v_fma_f32 v3, -v1, v2, 1.0
	v_fmac_f32_e32 v2, v3, v2
	v_div_scale_f32 v3, vcc, 1.0, v0, 1.0
	v_mul_f32_e32 v4, v3, v2
	v_fma_f32 v5, -v1, v4, v3
	v_fmac_f32_e32 v4, v5, v2
	v_fma_f32 v1, -v1, v4, v3
	v_div_fmas_f32 v1, v1, v2, v4
	v_div_fixup_f32 v4, v1, v0, 1.0
	v_mov_b64_e32 v[0:1], s[0:1]
	v_mad_u64_u32 v[0:1], s[0:1], v142, s8, v[0:1]
	v_mad_i32_i24 v1, v143, s8, v1
	s_mov_b64 s[8:9], 0x3e38aa3b
	s_lshl_b32 s0, s10, 1
	s_mov_b32 s1, s9
	s_movk_i32 s10, 0xeb00
	v_lshl_add_u64 v[2:3], v[0:1], 0, s[0:1]
	v_mad_u64_u32 v[0:1], s[8:9], v142, s10, v[0:1]
	v_mad_i32_i24 v1, v143, s10, v1
	v_sub_u32_e32 v1, v1, v142
	v_lshl_add_u64 v[6:7], v[0:1], 0, s[0:1]
	v_lshl_add_u64 v[2:3], v[2:3], 0, v[140:141]
	s_mov_b64 s[0:1], 0x3dd0b00
	v_lshl_add_u64 v[0:1], v[2:3], 0, s[0:1]
	v_lshl_add_u64 v[12:13], v[6:7], 0, v[140:141]
	s_mov_b64 s[0:1], 0xd210200
	v_lshl_add_u64 v[6:7], v[12:13], 0, s[0:1]
	s_mov_b32 s0, 0x3dd0000
	v_add_co_u32_e32 v2, vcc, s0, v2
	v_readlane_b32 s10, v254, 51
	s_nop 0
	v_addc_co_u32_e32 v3, vcc, 0, v3, vcc
	v_readlane_b32 s98, v253, 59
	v_readlane_b32 s99, v253, 60
	s_nop 1
	v_writelane_b32 v76, s98, 40
	v_writelane_b32 v77, s99, 40
	s_mov_b64 s[98:99], exec
	v_cmpx_eq_u32_e64 exec, 40, v234
	s_nop 3
	v_writelane_b32 v255, exec_hi, 41
	global_atomic_add v255, v[76:77], v251, off sc0
	s_mov_b64 exec, s[98:99]
	global_load_dwordx4 v[8:11], v[2:3], off offset:2816
	global_load_dwordx4 v[64:67], v[0:1], off offset:32
	global_load_dwordx4 v[68:71], v[0:1], off offset:64
	global_load_dwordx4 v[72:75], v[0:1], off offset:96
	s_waitcnt vmcnt(3)
	v_mov_b32_e32 v5, v10
	s_nop 1
	v_permlane32_swap_b32_e32 v8, v5
	v_lshlrev_b32_e32 v14, 16, v8
	v_and_b32_e32 v8, 0xffff0000, v8
	v_mov_b32_e32 v16, v11
	v_mul_f32_e32 v10, 0xbfb8aa3b, v14
	v_mul_f32_e32 v11, 0xbfb8aa3b, v8
	v_exp_f32_e32 v10, v10
	v_exp_f32_e32 v11, v11
	v_permlane32_swap_b32_e32 v9, v16
	v_pk_mul_f32 v[2:3], v[48:49], v[4:5] op_sel_hi:[1,0]
	v_pk_add_f32 v[10:11], v[10:11], 1.0 op_sel_hi:[1,0]
	s_nop 0
	v_div_scale_f32 v15, s[0:1], v11, v11, v8
	v_rcp_f32_e32 v17, v15
	s_nop 0
	v_fma_f32 v18, -v15, v17, 1.0
	v_fmac_f32_e32 v17, v18, v17
	v_div_scale_f32 v18, vcc, v8, v11, v8
	v_mul_f32_e32 v19, v18, v17
	v_fma_f32 v20, -v15, v19, v18
	v_fmac_f32_e32 v19, v20, v17
	v_fma_f32 v15, -v15, v19, v18
	v_div_fmas_f32 v15, v15, v17, v19
	v_div_fixup_f32 v11, v15, v11, v8
	v_div_scale_f32 v8, s[0:1], v10, v10, v14
	v_rcp_f32_e32 v15, v8
	s_nop 0
	v_fma_f32 v17, -v8, v15, 1.0
	v_fmac_f32_e32 v15, v17, v15
	v_div_scale_f32 v17, vcc, v14, v10, v14
	v_mul_f32_e32 v18, v17, v15
	v_fma_f32 v19, -v8, v18, v17
	v_fmac_f32_e32 v18, v19, v15
	v_fma_f32 v8, -v8, v18, v17
	v_div_fmas_f32 v8, v8, v15, v18
	v_div_fixup_f32 v10, v8, v10, v14
	v_lshlrev_b32_e32 v14, 16, v9
	v_and_b32_e32 v15, 0xffff0000, v9
	v_pk_mul_f32 v[2:3], v[2:3], v[10:11]
	v_mul_f32_e32 v10, 0xbfb8aa3b, v14
	v_mul_f32_e32 v11, 0xbfb8aa3b, v15
	v_exp_f32_e32 v10, v10
	v_exp_f32_e32 v11, v11
	v_pk_mul_f32 v[8:9], v[50:51], v[4:5] op_sel_hi:[1,0]
	v_pk_add_f32 v[10:11], v[10:11], 1.0 op_sel_hi:[1,0]
	s_nop 0
	v_div_scale_f32 v17, s[0:1], v11, v11, v15
	v_rcp_f32_e32 v18, v17
	s_nop 0
	v_fma_f32 v19, -v17, v18, 1.0
	v_fmac_f32_e32 v18, v19, v18
	v_div_scale_f32 v19, vcc, v15, v11, v15
	v_mul_f32_e32 v20, v19, v18
	v_fma_f32 v21, -v17, v20, v19
	v_fmac_f32_e32 v20, v21, v18
	v_fma_f32 v17, -v17, v20, v19
	v_div_fmas_f32 v17, v17, v18, v20
	v_div_fixup_f32 v11, v17, v11, v15
	v_div_scale_f32 v15, s[0:1], v10, v10, v14
	v_rcp_f32_e32 v17, v15
	s_nop 0
	v_fma_f32 v18, -v15, v17, 1.0
	v_fmac_f32_e32 v17, v18, v17
	v_div_scale_f32 v18, vcc, v14, v10, v14
	v_mul_f32_e32 v19, v18, v17
	v_fma_f32 v20, -v15, v19, v18
	v_fmac_f32_e32 v19, v20, v17
	v_fma_f32 v15, -v15, v19, v18
	v_div_fmas_f32 v15, v15, v17, v19
	v_lshlrev_b32_e32 v17, 16, v5
	v_and_b32_e32 v5, 0xffff0000, v5
	v_div_fixup_f32 v10, v15, v10, v14
	v_mul_f32_e32 v14, 0xbfb8aa3b, v17
	v_mul_f32_e32 v15, 0xbfb8aa3b, v5
	v_exp_f32_e32 v14, v14
	v_exp_f32_e32 v15, v15
	v_pk_mul_f32 v[10:11], v[8:9], v[10:11]
	v_pk_mul_f32 v[8:9], v[52:53], v[4:5] op_sel_hi:[1,0]
	v_pk_add_f32 v[14:15], v[14:15], 1.0 op_sel_hi:[1,0]
	s_nop 0
	v_div_scale_f32 v18, s[0:1], v15, v15, v5
	v_rcp_f32_e32 v19, v18
	s_nop 0
	v_fma_f32 v20, -v18, v19, 1.0
	v_fmac_f32_e32 v19, v20, v19
	v_div_scale_f32 v20, vcc, v5, v15, v5
	v_mul_f32_e32 v21, v20, v19
	v_fma_f32 v22, -v18, v21, v20
	v_fmac_f32_e32 v21, v22, v19
	v_fma_f32 v18, -v18, v21, v20
	v_div_fmas_f32 v18, v18, v19, v21
	v_div_fixup_f32 v15, v18, v15, v5
	v_div_scale_f32 v5, s[0:1], v14, v14, v17
	v_rcp_f32_e32 v18, v5
	s_nop 0
	v_fma_f32 v19, -v5, v18, 1.0
	v_fmac_f32_e32 v18, v19, v18
	v_div_scale_f32 v19, vcc, v17, v14, v17
	v_mul_f32_e32 v20, v19, v18
	v_fma_f32 v21, -v5, v20, v19
	v_fmac_f32_e32 v20, v21, v18
	v_fma_f32 v5, -v5, v20, v19
	v_div_fmas_f32 v5, v5, v18, v20
	v_div_fixup_f32 v14, v5, v14, v17
	v_lshlrev_b32_e32 v5, 16, v16
	v_and_b32_e32 v18, 0xffff0000, v16
	v_mul_f32_e32 v16, 0xbfb8aa3b, v5
	v_mul_f32_e32 v17, 0xbfb8aa3b, v18
	v_exp_f32_e32 v16, v16
	v_exp_f32_e32 v17, v17
	v_pk_mul_f32 v[14:15], v[8:9], v[14:15]
	v_pk_mul_f32 v[8:9], v[54:55], v[4:5] op_sel_hi:[1,0]
	v_pk_add_f32 v[16:17], v[16:17], 1.0 op_sel_hi:[1,0]
	s_nop 0
	v_div_scale_f32 v19, s[0:1], v17, v17, v18
	v_rcp_f32_e32 v20, v19
	s_nop 0
	v_fma_f32 v21, -v19, v20, 1.0
	v_fmac_f32_e32 v20, v21, v20
	v_div_scale_f32 v21, vcc, v18, v17, v18
	v_mul_f32_e32 v22, v21, v20
	v_fma_f32 v23, -v19, v22, v21
	v_fmac_f32_e32 v22, v23, v20
	v_fma_f32 v19, -v19, v22, v21
	v_div_fmas_f32 v19, v19, v20, v22
	v_div_fixup_f32 v17, v19, v17, v18
	v_div_scale_f32 v18, s[0:1], v16, v16, v5
	v_rcp_f32_e32 v19, v18
	s_mov_b32 s0, 0xd210000
	v_fma_f32 v20, -v18, v19, 1.0
	v_fmac_f32_e32 v19, v20, v19
	v_div_scale_f32 v20, vcc, v5, v16, v5
	v_mul_f32_e32 v21, v20, v19
	v_fma_f32 v22, -v18, v21, v20
	v_fmac_f32_e32 v21, v22, v19
	v_fma_f32 v18, -v18, v21, v20
	v_div_fmas_f32 v18, v18, v19, v21
	v_div_fixup_f32 v16, v18, v16, v5
	v_pk_mul_f32 v[16:17], v[8:9], v[16:17]
	v_cvt_pk_bf16_f32 v8, v2, v3
	v_cvt_pk_bf16_f32 v9, v10, v11
	v_cvt_pk_bf16_f32 v10, v14, v15
	v_cvt_pk_bf16_f32 v11, v16, v17
	v_add_co_u32_e32 v2, vcc, s0, v12
	v_permlane32_swap_b32_e32 v8, v10
	v_permlane32_swap_b32_e32 v9, v11
	v_addc_co_u32_e32 v3, vcc, 0, v13, vcc
	global_store_dwordx4 v[2:3], v[8:11], off offset:512
	s_waitcnt vmcnt(3)
	v_mov_b32_e32 v5, v66
	s_nop 1
	v_mov_b32_e32 v8, v64
	s_nop 1
	v_permlane32_swap_b32_e32 v8, v5
	v_lshlrev_b32_e32 v12, 16, v8
	v_and_b32_e32 v8, 0xffff0000, v8
	v_mov_b32_e32 v14, v67
	v_mul_f32_e32 v10, 0xbfb8aa3b, v12
	v_mul_f32_e32 v11, 0xbfb8aa3b, v8
	v_exp_f32_e32 v10, v10
	v_exp_f32_e32 v11, v11
	v_mov_b32_e32 v9, v65
	s_nop 1
	v_permlane32_swap_b32_e32 v9, v14
	v_pk_mul_f32 v[2:3], v[56:57], v[4:5] op_sel_hi:[1,0]
	v_pk_add_f32 v[10:11], v[10:11], 1.0 op_sel_hi:[1,0]
	s_nop 0
	v_div_scale_f32 v13, s[0:1], v11, v11, v8
	v_rcp_f32_e32 v15, v13
	s_nop 0
	v_fma_f32 v16, -v13, v15, 1.0
	v_fmac_f32_e32 v15, v16, v15
	v_div_scale_f32 v16, vcc, v8, v11, v8
	v_mul_f32_e32 v17, v16, v15
	v_fma_f32 v18, -v13, v17, v16
	v_fmac_f32_e32 v17, v18, v15
	v_fma_f32 v13, -v13, v17, v16
	v_div_fmas_f32 v13, v13, v15, v17
	v_div_fixup_f32 v11, v13, v11, v8
	v_div_scale_f32 v8, s[0:1], v10, v10, v12
	v_rcp_f32_e32 v13, v8
	s_nop 0
	v_fma_f32 v15, -v8, v13, 1.0
	v_fmac_f32_e32 v13, v15, v13
	v_div_scale_f32 v15, vcc, v12, v10, v12
	v_mul_f32_e32 v16, v15, v13
	v_fma_f32 v17, -v8, v16, v15
	v_fmac_f32_e32 v16, v17, v13
	v_fma_f32 v8, -v8, v16, v15
	v_div_fmas_f32 v8, v8, v13, v16
	v_div_fixup_f32 v10, v8, v10, v12
	v_lshlrev_b32_e32 v12, 16, v9
	v_and_b32_e32 v13, 0xffff0000, v9
	v_pk_mul_f32 v[2:3], v[2:3], v[10:11]
	v_mul_f32_e32 v10, 0xbfb8aa3b, v12
	v_mul_f32_e32 v11, 0xbfb8aa3b, v13
	v_exp_f32_e32 v10, v10
	v_exp_f32_e32 v11, v11
	v_pk_mul_f32 v[8:9], v[58:59], v[4:5] op_sel_hi:[1,0]
	v_pk_add_f32 v[10:11], v[10:11], 1.0 op_sel_hi:[1,0]
	s_nop 0
	v_div_scale_f32 v15, s[0:1], v11, v11, v13
	v_rcp_f32_e32 v16, v15
	s_nop 0
	v_fma_f32 v17, -v15, v16, 1.0
	v_fmac_f32_e32 v16, v17, v16
	v_div_scale_f32 v17, vcc, v13, v11, v13
	v_mul_f32_e32 v18, v17, v16
	v_fma_f32 v19, -v15, v18, v17
	v_fmac_f32_e32 v18, v19, v16
	v_fma_f32 v15, -v15, v18, v17
	v_div_fmas_f32 v15, v15, v16, v18
	v_div_fixup_f32 v11, v15, v11, v13
	v_div_scale_f32 v13, s[0:1], v10, v10, v12
	v_rcp_f32_e32 v15, v13
	s_nop 0
	v_fma_f32 v16, -v13, v15, 1.0
	v_fmac_f32_e32 v15, v16, v15
	v_div_scale_f32 v16, vcc, v12, v10, v12
	v_mul_f32_e32 v17, v16, v15
	v_fma_f32 v18, -v13, v17, v16
	v_fmac_f32_e32 v17, v18, v15
	v_fma_f32 v13, -v13, v17, v16
	v_div_fmas_f32 v13, v13, v15, v17
	v_lshlrev_b32_e32 v15, 16, v5
	v_and_b32_e32 v5, 0xffff0000, v5
	v_div_fixup_f32 v10, v13, v10, v12
	v_mul_f32_e32 v12, 0xbfb8aa3b, v15
	v_mul_f32_e32 v13, 0xbfb8aa3b, v5
	v_exp_f32_e32 v12, v12
	v_exp_f32_e32 v13, v13
	v_pk_mul_f32 v[10:11], v[8:9], v[10:11]
	v_pk_mul_f32 v[8:9], v[60:61], v[4:5] op_sel_hi:[1,0]
	v_pk_add_f32 v[12:13], v[12:13], 1.0 op_sel_hi:[1,0]
	s_nop 0
	v_div_scale_f32 v16, s[0:1], v13, v13, v5
	v_rcp_f32_e32 v17, v16
	s_nop 0
	v_fma_f32 v18, -v16, v17, 1.0
	v_fmac_f32_e32 v17, v18, v17
	v_div_scale_f32 v18, vcc, v5, v13, v5
	v_mul_f32_e32 v19, v18, v17
	v_fma_f32 v20, -v16, v19, v18
	v_fmac_f32_e32 v19, v20, v17
	v_fma_f32 v16, -v16, v19, v18
	v_div_fmas_f32 v16, v16, v17, v19
	v_div_fixup_f32 v13, v16, v13, v5
	v_div_scale_f32 v5, s[0:1], v12, v12, v15
	v_rcp_f32_e32 v16, v5
	s_nop 0
	v_fma_f32 v17, -v5, v16, 1.0
	v_fmac_f32_e32 v16, v17, v16
	v_div_scale_f32 v17, vcc, v15, v12, v15
	v_mul_f32_e32 v18, v17, v16
	v_fma_f32 v19, -v5, v18, v17
	v_fmac_f32_e32 v18, v19, v16
	v_fma_f32 v5, -v5, v18, v17
	v_div_fmas_f32 v5, v5, v16, v18
	v_div_fixup_f32 v12, v5, v12, v15
	v_lshlrev_b32_e32 v5, 16, v14
	v_and_b32_e32 v16, 0xffff0000, v14
	v_mul_f32_e32 v14, 0xbfb8aa3b, v5
	v_mul_f32_e32 v15, 0xbfb8aa3b, v16
	v_exp_f32_e32 v14, v14
	v_exp_f32_e32 v15, v15
	v_pk_mul_f32 v[12:13], v[8:9], v[12:13]
	v_pk_mul_f32 v[8:9], v[62:63], v[4:5] op_sel_hi:[1,0]
	v_pk_add_f32 v[14:15], v[14:15], 1.0 op_sel_hi:[1,0]
	s_nop 0
	v_div_scale_f32 v17, s[0:1], v15, v15, v16
	v_rcp_f32_e32 v18, v17
	s_nop 0
	v_fma_f32 v19, -v17, v18, 1.0
	v_fmac_f32_e32 v18, v19, v18
	v_div_scale_f32 v19, vcc, v16, v15, v16
	v_mul_f32_e32 v20, v19, v18
	v_fma_f32 v21, -v17, v20, v19
	v_fmac_f32_e32 v20, v21, v18
	v_fma_f32 v17, -v17, v20, v19
	v_div_fmas_f32 v17, v17, v18, v20
	v_div_fixup_f32 v15, v17, v15, v16
	v_div_scale_f32 v16, s[0:1], v14, v14, v5
	v_rcp_f32_e32 v17, v16
	s_nop 0
	v_fma_f32 v18, -v16, v17, 1.0
	v_fmac_f32_e32 v17, v18, v17
	v_div_scale_f32 v18, vcc, v5, v14, v5
	v_mul_f32_e32 v19, v18, v17
	v_fma_f32 v20, -v16, v19, v18
	v_fmac_f32_e32 v19, v20, v17
	v_fma_f32 v16, -v16, v19, v18
	v_div_fmas_f32 v16, v16, v17, v19
	v_div_fixup_f32 v14, v16, v14, v5
	v_pk_mul_f32 v[14:15], v[8:9], v[14:15]
	v_cvt_pk_bf16_f32 v8, v2, v3
	v_cvt_pk_bf16_f32 v9, v10, v11
	v_cvt_pk_bf16_f32 v10, v12, v13
	v_cvt_pk_bf16_f32 v11, v14, v15
	s_nop 0
	v_permlane32_swap_b32_e32 v8, v10
	v_permlane32_swap_b32_e32 v9, v11
	global_store_dwordx4 v[6:7], v[8:11], off offset:32
	s_waitcnt vmcnt(3)
	v_mov_b32_e32 v5, v70
	s_nop 1
	v_mov_b32_e32 v8, v68
	s_nop 1
	v_permlane32_swap_b32_e32 v8, v5
	v_lshlrev_b32_e32 v12, 16, v8
	v_and_b32_e32 v8, 0xffff0000, v8
	v_mov_b32_e32 v14, v71
	v_mul_f32_e32 v10, 0xbfb8aa3b, v12
	v_mul_f32_e32 v11, 0xbfb8aa3b, v8
	v_exp_f32_e32 v10, v10
	v_exp_f32_e32 v11, v11
	v_mov_b32_e32 v9, v69
	s_nop 1
	v_permlane32_swap_b32_e32 v9, v14
	v_pk_mul_f32 v[2:3], v[32:33], v[4:5] op_sel_hi:[1,0]
	v_pk_add_f32 v[10:11], v[10:11], 1.0 op_sel_hi:[1,0]
	s_nop 0
	v_div_scale_f32 v13, s[0:1], v11, v11, v8
	v_rcp_f32_e32 v15, v13
	s_nop 0
	v_fma_f32 v16, -v13, v15, 1.0
	v_fmac_f32_e32 v15, v16, v15
	v_div_scale_f32 v16, vcc, v8, v11, v8
	v_mul_f32_e32 v17, v16, v15
	v_fma_f32 v18, -v13, v17, v16
	v_fmac_f32_e32 v17, v18, v15
	v_fma_f32 v13, -v13, v17, v16
	v_div_fmas_f32 v13, v13, v15, v17
	v_div_fixup_f32 v11, v13, v11, v8
	v_div_scale_f32 v8, s[0:1], v10, v10, v12
	v_rcp_f32_e32 v13, v8
	s_nop 0
	v_fma_f32 v15, -v8, v13, 1.0
	v_fmac_f32_e32 v13, v15, v13
	v_div_scale_f32 v15, vcc, v12, v10, v12
	v_mul_f32_e32 v16, v15, v13
	v_fma_f32 v17, -v8, v16, v15
	v_fmac_f32_e32 v16, v17, v13
	v_fma_f32 v8, -v8, v16, v15
	v_div_fmas_f32 v8, v8, v13, v16
	v_div_fixup_f32 v10, v8, v10, v12
	v_lshlrev_b32_e32 v12, 16, v9
	v_and_b32_e32 v13, 0xffff0000, v9
	v_pk_mul_f32 v[2:3], v[2:3], v[10:11]
	v_mul_f32_e32 v10, 0xbfb8aa3b, v12
	v_mul_f32_e32 v11, 0xbfb8aa3b, v13
	v_exp_f32_e32 v10, v10
	v_exp_f32_e32 v11, v11
	v_pk_mul_f32 v[8:9], v[34:35], v[4:5] op_sel_hi:[1,0]
	v_pk_add_f32 v[10:11], v[10:11], 1.0 op_sel_hi:[1,0]
	s_nop 0
	v_div_scale_f32 v15, s[0:1], v11, v11, v13
	v_rcp_f32_e32 v16, v15
	s_nop 0
	v_fma_f32 v17, -v15, v16, 1.0
	v_fmac_f32_e32 v16, v17, v16
	v_div_scale_f32 v17, vcc, v13, v11, v13
	v_mul_f32_e32 v18, v17, v16
	v_fma_f32 v19, -v15, v18, v17
	v_fmac_f32_e32 v18, v19, v16
	v_fma_f32 v15, -v15, v18, v17
	v_div_fmas_f32 v15, v15, v16, v18
	v_div_fixup_f32 v11, v15, v11, v13
	v_div_scale_f32 v13, s[0:1], v10, v10, v12
	v_rcp_f32_e32 v15, v13
	s_nop 0
	v_fma_f32 v16, -v13, v15, 1.0
	v_fmac_f32_e32 v15, v16, v15
	v_div_scale_f32 v16, vcc, v12, v10, v12
	v_mul_f32_e32 v17, v16, v15
	v_fma_f32 v18, -v13, v17, v16
	v_fmac_f32_e32 v17, v18, v15
	v_fma_f32 v13, -v13, v17, v16
	v_div_fmas_f32 v13, v13, v15, v17
	v_lshlrev_b32_e32 v15, 16, v5
	v_and_b32_e32 v5, 0xffff0000, v5
	v_div_fixup_f32 v10, v13, v10, v12
	v_mul_f32_e32 v12, 0xbfb8aa3b, v15
	v_mul_f32_e32 v13, 0xbfb8aa3b, v5
	v_exp_f32_e32 v12, v12
	v_exp_f32_e32 v13, v13
	v_pk_mul_f32 v[10:11], v[8:9], v[10:11]
	v_pk_mul_f32 v[8:9], v[36:37], v[4:5] op_sel_hi:[1,0]
	v_pk_add_f32 v[12:13], v[12:13], 1.0 op_sel_hi:[1,0]
	s_nop 0
	v_div_scale_f32 v16, s[0:1], v13, v13, v5
	v_rcp_f32_e32 v17, v16
	s_nop 0
	v_fma_f32 v18, -v16, v17, 1.0
	v_fmac_f32_e32 v17, v18, v17
	v_div_scale_f32 v18, vcc, v5, v13, v5
	v_mul_f32_e32 v19, v18, v17
	v_fma_f32 v20, -v16, v19, v18
	v_fmac_f32_e32 v19, v20, v17
	v_fma_f32 v16, -v16, v19, v18
	v_div_fmas_f32 v16, v16, v17, v19
	v_div_fixup_f32 v13, v16, v13, v5
	v_div_scale_f32 v5, s[0:1], v12, v12, v15
	v_rcp_f32_e32 v16, v5
	s_nop 0
	v_fma_f32 v17, -v5, v16, 1.0
	v_fmac_f32_e32 v16, v17, v16
	v_div_scale_f32 v17, vcc, v15, v12, v15
	v_mul_f32_e32 v18, v17, v16
	v_fma_f32 v19, -v5, v18, v17
	v_fmac_f32_e32 v18, v19, v16
	v_fma_f32 v5, -v5, v18, v17
	v_div_fmas_f32 v5, v5, v16, v18
	v_div_fixup_f32 v12, v5, v12, v15
	v_lshlrev_b32_e32 v5, 16, v14
	v_and_b32_e32 v16, 0xffff0000, v14
	v_mul_f32_e32 v14, 0xbfb8aa3b, v5
	v_mul_f32_e32 v15, 0xbfb8aa3b, v16
	v_exp_f32_e32 v14, v14
	v_exp_f32_e32 v15, v15
	v_pk_mul_f32 v[12:13], v[8:9], v[12:13]
	v_pk_mul_f32 v[8:9], v[38:39], v[4:5] op_sel_hi:[1,0]
	v_pk_add_f32 v[14:15], v[14:15], 1.0 op_sel_hi:[1,0]
	s_nop 0
	v_div_scale_f32 v17, s[0:1], v15, v15, v16
	v_rcp_f32_e32 v18, v17
	s_nop 0
	v_fma_f32 v19, -v17, v18, 1.0
	v_fmac_f32_e32 v18, v19, v18
	v_div_scale_f32 v19, vcc, v16, v15, v16
	v_mul_f32_e32 v20, v19, v18
	v_fma_f32 v21, -v17, v20, v19
	v_fmac_f32_e32 v20, v21, v18
	v_fma_f32 v17, -v17, v20, v19
	v_div_fmas_f32 v17, v17, v18, v20
	v_div_fixup_f32 v15, v17, v15, v16
	v_div_scale_f32 v16, s[0:1], v14, v14, v5
	v_rcp_f32_e32 v17, v16
	s_nop 0
	v_fma_f32 v18, -v16, v17, 1.0
	v_fmac_f32_e32 v17, v18, v17
	v_div_scale_f32 v18, vcc, v5, v14, v5
	v_mul_f32_e32 v19, v18, v17
	v_fma_f32 v20, -v16, v19, v18
	v_fmac_f32_e32 v19, v20, v17
	v_fma_f32 v16, -v16, v19, v18
	v_div_fmas_f32 v16, v16, v17, v19
	v_div_fixup_f32 v14, v16, v14, v5
	v_pk_mul_f32 v[14:15], v[8:9], v[14:15]
	v_cvt_pk_bf16_f32 v8, v2, v3
	v_cvt_pk_bf16_f32 v9, v10, v11
	v_cvt_pk_bf16_f32 v10, v12, v13
	v_cvt_pk_bf16_f32 v11, v14, v15
	s_nop 0
	v_permlane32_swap_b32_e32 v8, v10
	v_permlane32_swap_b32_e32 v9, v11
	global_store_dwordx4 v[6:7], v[8:11], off offset:64
	s_waitcnt vmcnt(3)
	v_mov_b32_e32 v5, v74
	s_nop 1
	v_mov_b32_e32 v0, v72
	s_nop 1
	v_permlane32_swap_b32_e32 v0, v5
	v_lshlrev_b32_e32 v10, 16, v0
	v_and_b32_e32 v0, 0xffff0000, v0
	v_mul_f32_e32 v8, 0xbfb8aa3b, v10
	v_mul_f32_e32 v9, 0xbfb8aa3b, v0
	v_exp_f32_e32 v8, v8
	v_exp_f32_e32 v9, v9
	v_mov_b32_e32 v12, v75
	s_nop 1
	v_mov_b32_e32 v1, v73
	s_nop 1
	v_permlane32_swap_b32_e32 v1, v12
	v_pk_add_f32 v[8:9], v[8:9], 1.0 op_sel_hi:[1,0]
	v_pk_mul_f32 v[2:3], v[40:41], v[4:5] op_sel_hi:[1,0]
	v_div_scale_f32 v11, s[0:1], v9, v9, v0
	v_rcp_f32_e32 v13, v11
	s_nop 0
	v_fma_f32 v14, -v11, v13, 1.0
	v_fmac_f32_e32 v13, v14, v13
	v_div_scale_f32 v14, vcc, v0, v9, v0
	v_mul_f32_e32 v15, v14, v13
	v_fma_f32 v16, -v11, v15, v14
	v_fmac_f32_e32 v15, v16, v13
	v_fma_f32 v11, -v11, v15, v14
	v_div_fmas_f32 v11, v11, v13, v15
	v_div_fixup_f32 v9, v11, v9, v0
	v_div_scale_f32 v0, s[0:1], v8, v8, v10
	v_rcp_f32_e32 v11, v0
	s_nop 0
	v_fma_f32 v13, -v0, v11, 1.0
	v_fmac_f32_e32 v11, v13, v11
	v_div_scale_f32 v13, vcc, v10, v8, v10
	v_mul_f32_e32 v14, v13, v11
	v_fma_f32 v15, -v0, v14, v13
	v_fmac_f32_e32 v14, v15, v11
	v_fma_f32 v0, -v0, v14, v13
	v_div_fmas_f32 v0, v0, v11, v14
	v_div_fixup_f32 v8, v0, v8, v10
	v_lshlrev_b32_e32 v10, 16, v1
	v_and_b32_e32 v11, 0xffff0000, v1
	v_pk_mul_f32 v[2:3], v[2:3], v[8:9]
	v_mul_f32_e32 v8, 0xbfb8aa3b, v10
	v_mul_f32_e32 v9, 0xbfb8aa3b, v11
	v_exp_f32_e32 v8, v8
	v_exp_f32_e32 v9, v9
	v_pk_mul_f32 v[0:1], v[42:43], v[4:5] op_sel_hi:[1,0]
	v_pk_add_f32 v[8:9], v[8:9], 1.0 op_sel_hi:[1,0]
	s_nop 0
	v_div_scale_f32 v13, s[0:1], v9, v9, v11
	v_rcp_f32_e32 v14, v13
	s_nop 0
	v_fma_f32 v15, -v13, v14, 1.0
	v_fmac_f32_e32 v14, v15, v14
	v_div_scale_f32 v15, vcc, v11, v9, v11
	v_mul_f32_e32 v16, v15, v14
	v_fma_f32 v17, -v13, v16, v15
	v_fmac_f32_e32 v16, v17, v14
	v_fma_f32 v13, -v13, v16, v15
	v_div_fmas_f32 v13, v13, v14, v16
	v_div_fixup_f32 v9, v13, v9, v11
	v_div_scale_f32 v11, s[0:1], v8, v8, v10
	v_rcp_f32_e32 v13, v11
	s_nop 0
	v_fma_f32 v14, -v11, v13, 1.0
	v_fmac_f32_e32 v13, v14, v13
	v_div_scale_f32 v14, vcc, v10, v8, v10
	v_mul_f32_e32 v15, v14, v13
	v_fma_f32 v16, -v11, v15, v14
	v_fmac_f32_e32 v15, v16, v13
	v_fma_f32 v11, -v11, v15, v14
	v_div_fmas_f32 v11, v11, v13, v15
	v_lshlrev_b32_e32 v13, 16, v5
	v_and_b32_e32 v5, 0xffff0000, v5
	v_div_fixup_f32 v8, v11, v8, v10
	v_mul_f32_e32 v10, 0xbfb8aa3b, v13
	v_mul_f32_e32 v11, 0xbfb8aa3b, v5
	v_exp_f32_e32 v10, v10
	v_exp_f32_e32 v11, v11
	v_pk_mul_f32 v[8:9], v[0:1], v[8:9]
	v_pk_mul_f32 v[0:1], v[44:45], v[4:5] op_sel_hi:[1,0]
	v_pk_add_f32 v[10:11], v[10:11], 1.0 op_sel_hi:[1,0]
	s_nop 0
	v_div_scale_f32 v14, s[0:1], v11, v11, v5
	v_rcp_f32_e32 v15, v14
	s_nop 0
	v_fma_f32 v16, -v14, v15, 1.0
	v_fmac_f32_e32 v15, v16, v15
	v_div_scale_f32 v16, vcc, v5, v11, v5
	v_mul_f32_e32 v17, v16, v15
	v_fma_f32 v18, -v14, v17, v16
	v_fmac_f32_e32 v17, v18, v15
	v_fma_f32 v14, -v14, v17, v16
	v_div_fmas_f32 v14, v14, v15, v17
	v_div_fixup_f32 v11, v14, v11, v5
	v_div_scale_f32 v5, s[0:1], v10, v10, v13
	v_rcp_f32_e32 v14, v5
	s_nop 0
	v_fma_f32 v15, -v5, v14, 1.0
	v_fmac_f32_e32 v14, v15, v14
	v_div_scale_f32 v15, vcc, v13, v10, v13
	v_mul_f32_e32 v16, v15, v14
	v_fma_f32 v17, -v5, v16, v15
	v_fmac_f32_e32 v16, v17, v14
	v_fma_f32 v5, -v5, v16, v15
	v_div_fmas_f32 v5, v5, v14, v16
	v_div_fixup_f32 v10, v5, v10, v13
	v_lshlrev_b32_e32 v13, 16, v12
	v_and_b32_e32 v12, 0xffff0000, v12
	v_pk_mul_f32 v[10:11], v[0:1], v[10:11]
	v_pk_mul_f32 v[0:1], v[46:47], v[4:5] op_sel_hi:[1,0]
	v_mul_f32_e32 v4, 0xbfb8aa3b, v13
	v_mul_f32_e32 v5, 0xbfb8aa3b, v12
	v_exp_f32_e32 v4, v4
	v_exp_f32_e32 v5, v5
	s_nop 0
	v_pk_add_f32 v[4:5], v[4:5], 1.0 op_sel_hi:[1,0]
	s_nop 0
	v_div_scale_f32 v14, s[0:1], v5, v5, v12
	v_rcp_f32_e32 v15, v14
	s_nop 0
	v_fma_f32 v16, -v14, v15, 1.0
	v_fmac_f32_e32 v15, v16, v15
	v_div_scale_f32 v16, vcc, v12, v5, v12
	v_mul_f32_e32 v17, v16, v15
	v_fma_f32 v18, -v14, v17, v16
	v_fmac_f32_e32 v17, v18, v15
	v_fma_f32 v14, -v14, v17, v16
	v_div_fmas_f32 v14, v14, v15, v17
	v_div_fixup_f32 v5, v14, v5, v12
	v_div_scale_f32 v12, s[0:1], v4, v4, v13
	v_rcp_f32_e32 v14, v12
	s_nop 0
	v_fma_f32 v15, -v12, v14, 1.0
	v_fmac_f32_e32 v14, v15, v14
	v_div_scale_f32 v15, vcc, v13, v4, v13
	v_mul_f32_e32 v16, v15, v14
	v_fma_f32 v17, -v12, v16, v15
	v_fmac_f32_e32 v16, v17, v14
	v_fma_f32 v12, -v12, v16, v15
	v_div_fmas_f32 v12, v12, v14, v16
	v_div_fixup_f32 v4, v12, v4, v13
	v_pk_mul_f32 v[4:5], v[0:1], v[4:5]
	v_cvt_pk_bf16_f32 v0, v2, v3
	v_cvt_pk_bf16_f32 v1, v8, v9
	v_cvt_pk_bf16_f32 v2, v10, v11
	v_cvt_pk_bf16_f32 v3, v4, v5
	s_nop 0
	v_permlane32_swap_b32_e32 v0, v2
	v_permlane32_swap_b32_e32 v1, v3
	global_store_dwordx4 v[6:7], v[0:3], off offset:96
	s_branch .LBB0_476

.LBB0_475:
	v_lshlrev_b32_e32 v0, 16, v199
	v_mul_f32_e32 v0, 0xbfb8aa3b, v0
	v_exp_f32_e32 v0, v0
	v_lshlrev_b64 v[10:11], 11, v[200:201]
	v_lshlrev_b32_e32 v192, 1, v235
	v_readlane_b32 s10, v254, 51
	v_add_f32_e32 v0, 1.0, v0
	v_div_scale_f32 v1, s[0:1], v0, v0, 1.0
	v_rcp_f32_e32 v2, v1
	s_nop 0
	v_fma_f32 v3, -v1, v2, 1.0
	v_fmac_f32_e32 v2, v3, v2
	v_div_scale_f32 v3, vcc, 1.0, v0, 1.0
	v_mul_f32_e32 v4, v3, v2
	v_fma_f32 v5, -v1, v4, v3
	v_fmac_f32_e32 v4, v5, v2
	v_fma_f32 v1, -v1, v4, v3
	v_div_fmas_f32 v1, v1, v2, v4
	v_div_fixup_f32 v4, v1, v0, 1.0
	v_and_b32_e32 v0, 0xffff0000, v199
	v_mul_f32_e32 v0, 0xbfb8aa3b, v0
	v_exp_f32_e32 v206, v0
	s_waitcnt lgkmcnt(0)
	v_pk_add_f32 v[0:1], v[206:207], v[194:195]
	s_nop 0
	v_div_scale_f32 v2, s[0:1], v0, v0, 1.0
	v_rcp_f32_e32 v3, v2
	ds_bpermute_b32 v195, v236, v209
	v_fma_f32 v5, -v2, v3, 1.0
	v_fmac_f32_e32 v3, v5, v3
	v_div_scale_f32 v5, vcc, 1.0, v0, 1.0
	v_mul_f32_e32 v6, v5, v3
	v_fma_f32 v7, -v2, v6, v5
	v_fmac_f32_e32 v6, v7, v3
	v_fma_f32 v2, -v2, v6, v5
	v_div_fmas_f32 v2, v2, v3, v6
	v_div_fixup_f32 v0, v2, v0, 1.0
	v_div_scale_f32 v2, s[0:1], v1, v1, v0
	v_rcp_f32_e32 v3, v2
	s_nop 0
	v_fma_f32 v5, -v2, v3, 1.0
	v_fmac_f32_e32 v3, v5, v3
	v_div_scale_f32 v5, vcc, v0, v1, v0
	v_mul_f32_e32 v6, v5, v3
	v_fma_f32 v7, -v2, v6, v5
	v_fmac_f32_e32 v6, v7, v3
	v_fma_f32 v2, -v2, v6, v5
	v_div_fmas_f32 v2, v2, v3, v6
	v_div_fixup_f32 v6, v2, v1, v0
	v_lshlrev_b32_e32 v0, 16, v197
	v_mul_f32_e32 v0, 0xbfb8aa3b, v0
	v_exp_f32_e32 v208, v0
	s_waitcnt lgkmcnt(0)
	v_pk_add_f32 v[0:1], v[208:209], v[194:195]
	s_nop 0
	v_div_scale_f32 v2, s[0:1], v0, v0, 1.0
	v_rcp_f32_e32 v3, v2
	s_nop 0
	v_fma_f32 v5, -v2, v3, 1.0
	v_fmac_f32_e32 v3, v5, v3
	v_div_scale_f32 v5, vcc, 1.0, v0, 1.0
	v_mul_f32_e32 v7, v5, v3
	v_fma_f32 v8, -v2, v7, v5
	v_fmac_f32_e32 v7, v8, v3
	v_fma_f32 v2, -v2, v7, v5
	v_div_fmas_f32 v2, v2, v3, v7
	v_div_fixup_f32 v0, v2, v0, 1.0
	v_div_scale_f32 v2, s[0:1], v1, v1, v0
	v_rcp_f32_e32 v3, v2
	v_readlane_b32 s0, v254, 43
	v_readlane_b32 s1, v254, 44
	v_fma_f32 v5, -v2, v3, 1.0
	v_fmac_f32_e32 v3, v5, v3
	v_div_scale_f32 v5, vcc, v0, v1, v0
	v_mul_f32_e32 v7, v5, v3
	v_fma_f32 v8, -v2, v7, v5
	v_fmac_f32_e32 v7, v8, v3
	v_fma_f32 v2, -v2, v7, v5
	v_div_fmas_f32 v2, v2, v3, v7
	v_div_fixup_f32 v8, v2, v1, v0
	v_lshlrev_b64 v[0:1], 1, v[204:205]
	v_lshl_add_u64 v[2:3], v[202:203], 0, v[0:1]
	v_lshl_add_u64 v[10:11], s[0:1], 0, v[10:11]
	v_lshl_add_u64 v[10:11], v[10:11], 0, v[0:1]
	v_lshl_add_u64 v[2:3], v[2:3], 0, v[192:193]
	s_mov_b64 s[0:1], 0x1200
	v_lshl_add_u64 v[0:1], v[2:3], 0, s[0:1]
	v_lshl_add_u64 v[16:17], v[10:11], 0, v[192:193]
	s_mov_b64 s[0:1], 0xd210400
	v_lshl_add_u64 v[10:11], v[16:17], 0, s[0:1]
	s_movk_i32 s0, 0x1000
	v_add_co_u32_e32 v2, vcc, s0, v2
	s_nop 1
	v_addc_co_u32_e32 v3, vcc, 0, v3, vcc
	v_readlane_b32 s98, v253, 59
	v_readlane_b32 s99, v253, 60
	s_nop 1
	v_writelane_b32 v140, s98, 40
	v_writelane_b32 v141, s99, 40
	s_mov_b64 s[98:99], exec
	v_cmpx_eq_u32_e64 exec, 40, v234
	s_nop 3
	v_writelane_b32 v255, exec_hi, 41
	global_atomic_add v255, v[140:141], v251, off sc0
	s_mov_b64 exec, s[98:99]
	global_load_dwordx4 v[12:15], v[2:3], off offset:512
	global_load_dwordx4 v[128:131], v[0:1], off offset:32
	global_load_dwordx4 v[132:135], v[0:1], off offset:64
	global_load_dwordx4 v[136:139], v[0:1], off offset:96
	s_waitcnt vmcnt(3)
	v_mov_b32_e32 v5, v14
	s_nop 1
	v_permlane32_swap_b32_e32 v12, v5
	v_lshlrev_b32_e32 v9, 16, v12
	v_and_b32_e32 v12, 0xffff0000, v12
	v_mov_b32_e32 v7, v15
	v_mul_f32_e32 v14, 0xbfb8aa3b, v9
	v_mul_f32_e32 v15, 0xbfb8aa3b, v12
	v_exp_f32_e32 v14, v14
	v_exp_f32_e32 v15, v15
	v_permlane32_swap_b32_e32 v13, v7
	v_pk_mul_f32 v[2:3], v[96:97], v[6:7] op_sel_hi:[1,0]
	v_pk_add_f32 v[14:15], v[14:15], 1.0 op_sel_hi:[1,0]
	v_pk_fma_f32 v[2:3], v[4:5], v[80:81], v[2:3] op_sel_hi:[0,1,1]
	v_div_scale_f32 v18, s[0:1], v15, v15, v12
	v_rcp_f32_e32 v19, v18
	v_pk_fma_f32 v[2:3], v[112:113], v[8:9], v[2:3] op_sel_hi:[1,0,1]
	v_fma_f32 v20, -v18, v19, 1.0
	v_fmac_f32_e32 v19, v20, v19
	v_div_scale_f32 v20, vcc, v12, v15, v12
	v_mul_f32_e32 v21, v20, v19
	v_fma_f32 v22, -v18, v21, v20
	v_fmac_f32_e32 v21, v22, v19
	v_fma_f32 v18, -v18, v21, v20
	v_div_fmas_f32 v18, v18, v19, v21
	v_div_fixup_f32 v15, v18, v15, v12
	v_div_scale_f32 v12, s[0:1], v14, v14, v9
	v_rcp_f32_e32 v18, v12
	s_nop 0
	v_fma_f32 v19, -v12, v18, 1.0
	v_fmac_f32_e32 v18, v19, v18
	v_div_scale_f32 v19, vcc, v9, v14, v9
	v_mul_f32_e32 v20, v19, v18
	v_fma_f32 v21, -v12, v20, v19
	v_fmac_f32_e32 v20, v21, v18
	v_fma_f32 v12, -v12, v20, v19
	v_div_fmas_f32 v12, v12, v18, v20
	v_div_fixup_f32 v14, v12, v14, v9
	v_lshlrev_b32_e32 v9, 16, v13
	v_and_b32_e32 v18, 0xffff0000, v13
	v_pk_mul_f32 v[2:3], v[2:3], v[14:15]
	v_mul_f32_e32 v14, 0xbfb8aa3b, v9
	v_mul_f32_e32 v15, 0xbfb8aa3b, v18
	v_exp_f32_e32 v14, v14
	v_exp_f32_e32 v15, v15
	v_pk_mul_f32 v[12:13], v[98:99], v[6:7] op_sel_hi:[1,0]
	v_pk_add_f32 v[14:15], v[14:15], 1.0 op_sel_hi:[1,0]
	s_nop 0
	v_div_scale_f32 v19, s[0:1], v15, v15, v18
	v_rcp_f32_e32 v20, v19
	v_pk_fma_f32 v[12:13], v[4:5], v[82:83], v[12:13] op_sel_hi:[0,1,1]
	v_pk_fma_f32 v[12:13], v[114:115], v[8:9], v[12:13] op_sel_hi:[1,0,1]
	v_fma_f32 v21, -v19, v20, 1.0
	v_fmac_f32_e32 v20, v21, v20
	v_div_scale_f32 v21, vcc, v18, v15, v18
	v_mul_f32_e32 v22, v21, v20
	v_fma_f32 v23, -v19, v22, v21
	v_fmac_f32_e32 v22, v23, v20
	v_fma_f32 v19, -v19, v22, v21
	v_div_fmas_f32 v19, v19, v20, v22
	v_div_fixup_f32 v15, v19, v15, v18
	v_div_scale_f32 v18, s[0:1], v14, v14, v9
	v_rcp_f32_e32 v19, v18
	s_nop 0
	v_fma_f32 v20, -v18, v19, 1.0
	v_fmac_f32_e32 v19, v20, v19
	v_div_scale_f32 v20, vcc, v9, v14, v9
	v_mul_f32_e32 v21, v20, v19
	v_fma_f32 v22, -v18, v21, v20
	v_fmac_f32_e32 v21, v22, v19
	v_fma_f32 v18, -v18, v21, v20
	v_div_fmas_f32 v18, v18, v19, v21
	v_div_fixup_f32 v14, v18, v14, v9
	v_lshlrev_b32_e32 v9, 16, v5
	v_and_b32_e32 v5, 0xffff0000, v5
	v_mul_f32_e32 v18, 0xbfb8aa3b, v9
	v_mul_f32_e32 v19, 0xbfb8aa3b, v5
	v_exp_f32_e32 v18, v18
	v_exp_f32_e32 v19, v19
	v_pk_mul_f32 v[14:15], v[12:13], v[14:15]
	v_pk_mul_f32 v[12:13], v[100:101], v[6:7] op_sel_hi:[1,0]
	v_pk_add_f32 v[18:19], v[18:19], 1.0 op_sel_hi:[1,0]
	s_nop 0
	v_div_scale_f32 v20, s[0:1], v19, v19, v5
	v_rcp_f32_e32 v21, v20
	v_pk_fma_f32 v[12:13], v[4:5], v[84:85], v[12:13] op_sel_hi:[0,1,1]
	v_pk_fma_f32 v[12:13], v[116:117], v[8:9], v[12:13] op_sel_hi:[1,0,1]
	v_fma_f32 v22, -v20, v21, 1.0
	v_fmac_f32_e32 v21, v22, v21
	v_div_scale_f32 v22, vcc, v5, v19, v5
	v_mul_f32_e32 v23, v22, v21
	v_fma_f32 v24, -v20, v23, v22
	v_fmac_f32_e32 v23, v24, v21
	v_fma_f32 v20, -v20, v23, v22
	v_div_fmas_f32 v20, v20, v21, v23
	v_div_fixup_f32 v19, v20, v19, v5
	v_div_scale_f32 v5, s[0:1], v18, v18, v9
	v_rcp_f32_e32 v20, v5
	s_nop 0
	v_fma_f32 v21, -v5, v20, 1.0
	v_fmac_f32_e32 v20, v21, v20
	v_div_scale_f32 v21, vcc, v9, v18, v9
	v_mul_f32_e32 v22, v21, v20
	v_fma_f32 v23, -v5, v22, v21
	v_fmac_f32_e32 v22, v23, v20
	v_fma_f32 v5, -v5, v22, v21
	v_div_fmas_f32 v5, v5, v20, v22
	v_div_fixup_f32 v18, v5, v18, v9
	v_lshlrev_b32_e32 v5, 16, v7
	v_and_b32_e32 v7, 0xffff0000, v7
	v_pk_mul_f32 v[18:19], v[12:13], v[18:19]
	v_pk_mul_f32 v[12:13], v[102:103], v[6:7] op_sel_hi:[1,0]
	s_nop 0
	v_pk_fma_f32 v[12:13], v[4:5], v[86:87], v[12:13] op_sel_hi:[0,1,1]
	v_pk_fma_f32 v[12:13], v[118:119], v[8:9], v[12:13] op_sel_hi:[1,0,1]
	v_mul_f32_e32 v9, 0xbfb8aa3b, v5
	v_exp_f32_e32 v20, v9
	v_mul_f32_e32 v9, 0xbfb8aa3b, v7
	v_exp_f32_e32 v21, v9
	s_nop 0
	v_pk_add_f32 v[20:21], v[20:21], 1.0 op_sel_hi:[1,0]
	s_nop 0
	v_div_scale_f32 v9, s[0:1], v21, v21, v7
	v_rcp_f32_e32 v22, v9
	s_nop 0
	v_fma_f32 v23, -v9, v22, 1.0
	v_fmac_f32_e32 v22, v23, v22
	v_div_scale_f32 v23, vcc, v7, v21, v7
	v_mul_f32_e32 v24, v23, v22
	v_fma_f32 v25, -v9, v24, v23
	v_fmac_f32_e32 v24, v25, v22
	v_fma_f32 v9, -v9, v24, v23
	v_div_fmas_f32 v9, v9, v22, v24
	v_div_fixup_f32 v21, v9, v21, v7
	v_div_scale_f32 v7, s[0:1], v20, v20, v5
	v_rcp_f32_e32 v9, v7
	s_mov_b32 s0, 0xd210000
	v_fma_f32 v22, -v7, v9, 1.0
	v_fmac_f32_e32 v9, v22, v9
	v_div_scale_f32 v22, vcc, v5, v20, v5
	v_mul_f32_e32 v23, v22, v9
	v_fma_f32 v24, -v7, v23, v22
	v_fmac_f32_e32 v23, v24, v9
	v_fma_f32 v7, -v7, v23, v22
	v_div_fmas_f32 v7, v7, v9, v23
	v_div_fixup_f32 v20, v7, v20, v5
	v_pk_mul_f32 v[20:21], v[12:13], v[20:21]
	v_cvt_pk_bf16_f32 v12, v2, v3
	v_cvt_pk_bf16_f32 v13, v14, v15
	v_cvt_pk_bf16_f32 v14, v18, v19
	v_cvt_pk_bf16_f32 v15, v20, v21
	v_add_co_u32_e32 v2, vcc, s0, v16
	v_permlane32_swap_b32_e32 v12, v14
	v_permlane32_swap_b32_e32 v13, v15
	v_addc_co_u32_e32 v3, vcc, 0, v17, vcc
	global_store_dwordx4 v[2:3], v[12:15], off offset:1024
	s_waitcnt vmcnt(3)
	v_mov_b32_e32 v5, v130
	s_nop 1
	v_mov_b32_e32 v12, v128
	s_nop 1
	v_permlane32_swap_b32_e32 v12, v5
	v_lshlrev_b32_e32 v9, 16, v12
	v_and_b32_e32 v12, 0xffff0000, v12
	v_mov_b32_e32 v7, v131
	v_mul_f32_e32 v14, 0xbfb8aa3b, v9
	v_mul_f32_e32 v15, 0xbfb8aa3b, v12
	v_exp_f32_e32 v14, v14
	v_exp_f32_e32 v15, v15
	v_mov_b32_e32 v13, v129
	s_nop 1
	v_permlane32_swap_b32_e32 v13, v7
	v_pk_mul_f32 v[2:3], v[104:105], v[6:7] op_sel_hi:[1,0]
	v_pk_add_f32 v[14:15], v[14:15], 1.0 op_sel_hi:[1,0]
	v_pk_fma_f32 v[2:3], v[4:5], v[88:89], v[2:3] op_sel_hi:[0,1,1]
	v_div_scale_f32 v16, s[0:1], v15, v15, v12
	v_rcp_f32_e32 v17, v16
	v_pk_fma_f32 v[2:3], v[120:121], v[8:9], v[2:3] op_sel_hi:[1,0,1]
	v_fma_f32 v18, -v16, v17, 1.0
	v_fmac_f32_e32 v17, v18, v17
	v_div_scale_f32 v18, vcc, v12, v15, v12
	v_mul_f32_e32 v19, v18, v17
	v_fma_f32 v20, -v16, v19, v18
	v_fmac_f32_e32 v19, v20, v17
	v_fma_f32 v16, -v16, v19, v18
	v_div_fmas_f32 v16, v16, v17, v19
	v_div_fixup_f32 v15, v16, v15, v12
	v_div_scale_f32 v12, s[0:1], v14, v14, v9
	v_rcp_f32_e32 v16, v12
	s_nop 0
	v_fma_f32 v17, -v12, v16, 1.0
	v_fmac_f32_e32 v16, v17, v16
	v_div_scale_f32 v17, vcc, v9, v14, v9
	v_mul_f32_e32 v18, v17, v16
	v_fma_f32 v19, -v12, v18, v17
	v_fmac_f32_e32 v18, v19, v16
	v_fma_f32 v12, -v12, v18, v17
	v_div_fmas_f32 v12, v12, v16, v18
	v_div_fixup_f32 v14, v12, v14, v9
	v_lshlrev_b32_e32 v9, 16, v13
	v_and_b32_e32 v16, 0xffff0000, v13
	v_pk_mul_f32 v[2:3], v[2:3], v[14:15]
	v_mul_f32_e32 v14, 0xbfb8aa3b, v9
	v_mul_f32_e32 v15, 0xbfb8aa3b, v16
	v_exp_f32_e32 v14, v14
	v_exp_f32_e32 v15, v15
	v_pk_mul_f32 v[12:13], v[106:107], v[6:7] op_sel_hi:[1,0]
	v_pk_add_f32 v[14:15], v[14:15], 1.0 op_sel_hi:[1,0]
	s_nop 0
	v_div_scale_f32 v17, s[0:1], v15, v15, v16
	v_rcp_f32_e32 v18, v17
	v_pk_fma_f32 v[12:13], v[4:5], v[90:91], v[12:13] op_sel_hi:[0,1,1]
	v_pk_fma_f32 v[12:13], v[122:123], v[8:9], v[12:13] op_sel_hi:[1,0,1]
	v_fma_f32 v19, -v17, v18, 1.0
	v_fmac_f32_e32 v18, v19, v18
	v_div_scale_f32 v19, vcc, v16, v15, v16
	v_mul_f32_e32 v20, v19, v18
	v_fma_f32 v21, -v17, v20, v19
	v_fmac_f32_e32 v20, v21, v18
	v_fma_f32 v17, -v17, v20, v19
	v_div_fmas_f32 v17, v17, v18, v20
	v_div_fixup_f32 v15, v17, v15, v16
	v_div_scale_f32 v16, s[0:1], v14, v14, v9
	v_rcp_f32_e32 v17, v16
	s_nop 0
	v_fma_f32 v18, -v16, v17, 1.0
	v_fmac_f32_e32 v17, v18, v17
	v_div_scale_f32 v18, vcc, v9, v14, v9
	v_mul_f32_e32 v19, v18, v17
	v_fma_f32 v20, -v16, v19, v18
	v_fmac_f32_e32 v19, v20, v17
	v_fma_f32 v16, -v16, v19, v18
	v_div_fmas_f32 v16, v16, v17, v19
	v_div_fixup_f32 v14, v16, v14, v9
	v_lshlrev_b32_e32 v9, 16, v5
	v_and_b32_e32 v5, 0xffff0000, v5
	v_mul_f32_e32 v16, 0xbfb8aa3b, v9
	v_mul_f32_e32 v17, 0xbfb8aa3b, v5
	v_exp_f32_e32 v16, v16
	v_exp_f32_e32 v17, v17
	v_pk_mul_f32 v[14:15], v[12:13], v[14:15]
	v_pk_mul_f32 v[12:13], v[108:109], v[6:7] op_sel_hi:[1,0]
	v_pk_add_f32 v[16:17], v[16:17], 1.0 op_sel_hi:[1,0]
	s_nop 0
	v_div_scale_f32 v18, s[0:1], v17, v17, v5
	v_rcp_f32_e32 v19, v18
	v_pk_fma_f32 v[12:13], v[4:5], v[92:93], v[12:13] op_sel_hi:[0,1,1]
	v_pk_fma_f32 v[12:13], v[124:125], v[8:9], v[12:13] op_sel_hi:[1,0,1]
	v_fma_f32 v20, -v18, v19, 1.0
	v_fmac_f32_e32 v19, v20, v19
	v_div_scale_f32 v20, vcc, v5, v17, v5
	v_mul_f32_e32 v21, v20, v19
	v_fma_f32 v22, -v18, v21, v20
	v_fmac_f32_e32 v21, v22, v19
	v_fma_f32 v18, -v18, v21, v20
	v_div_fmas_f32 v18, v18, v19, v21
	v_div_fixup_f32 v17, v18, v17, v5
	v_div_scale_f32 v5, s[0:1], v16, v16, v9
	v_rcp_f32_e32 v18, v5
	s_nop 0
	v_fma_f32 v19, -v5, v18, 1.0
	v_fmac_f32_e32 v18, v19, v18
	v_div_scale_f32 v19, vcc, v9, v16, v9
	v_mul_f32_e32 v20, v19, v18
	v_fma_f32 v21, -v5, v20, v19
	v_fmac_f32_e32 v20, v21, v18
	v_fma_f32 v5, -v5, v20, v19
	v_div_fmas_f32 v5, v5, v18, v20
	v_div_fixup_f32 v16, v5, v16, v9
	v_lshlrev_b32_e32 v5, 16, v7
	v_and_b32_e32 v7, 0xffff0000, v7
	v_pk_mul_f32 v[16:17], v[12:13], v[16:17]
	v_pk_mul_f32 v[12:13], v[110:111], v[6:7] op_sel_hi:[1,0]
	s_nop 0
	v_pk_fma_f32 v[12:13], v[4:5], v[94:95], v[12:13] op_sel_hi:[0,1,1]
	v_pk_fma_f32 v[12:13], v[126:127], v[8:9], v[12:13] op_sel_hi:[1,0,1]
	v_mul_f32_e32 v9, 0xbfb8aa3b, v5
	v_exp_f32_e32 v18, v9
	v_mul_f32_e32 v9, 0xbfb8aa3b, v7
	v_exp_f32_e32 v19, v9
	s_nop 0
	v_pk_add_f32 v[18:19], v[18:19], 1.0 op_sel_hi:[1,0]
	s_nop 0
	v_div_scale_f32 v9, s[0:1], v19, v19, v7
	v_rcp_f32_e32 v20, v9
	s_nop 0
	v_fma_f32 v21, -v9, v20, 1.0
	v_fmac_f32_e32 v20, v21, v20
	v_div_scale_f32 v21, vcc, v7, v19, v7
	v_mul_f32_e32 v22, v21, v20
	v_fma_f32 v23, -v9, v22, v21
	v_fmac_f32_e32 v22, v23, v20
	v_fma_f32 v9, -v9, v22, v21
	v_div_fmas_f32 v9, v9, v20, v22
	v_div_fixup_f32 v19, v9, v19, v7
	v_div_scale_f32 v7, s[0:1], v18, v18, v5
	v_rcp_f32_e32 v9, v7
	s_nop 0
	v_fma_f32 v20, -v7, v9, 1.0
	v_fmac_f32_e32 v9, v20, v9
	v_div_scale_f32 v20, vcc, v5, v18, v5
	v_mul_f32_e32 v21, v20, v9
	v_fma_f32 v22, -v7, v21, v20
	v_fmac_f32_e32 v21, v22, v9
	v_fma_f32 v7, -v7, v21, v20
	v_div_fmas_f32 v7, v7, v9, v21
	v_div_fixup_f32 v18, v7, v18, v5
	v_pk_mul_f32 v[18:19], v[12:13], v[18:19]
	v_cvt_pk_bf16_f32 v12, v2, v3
	v_cvt_pk_bf16_f32 v13, v14, v15
	v_cvt_pk_bf16_f32 v14, v16, v17
	v_cvt_pk_bf16_f32 v15, v18, v19
	s_nop 0
	v_permlane32_swap_b32_e32 v12, v14
	v_permlane32_swap_b32_e32 v13, v15
	global_store_dwordx4 v[10:11], v[12:15], off offset:32
	s_waitcnt vmcnt(3)
	v_mov_b32_e32 v5, v134
	s_nop 1
	v_mov_b32_e32 v12, v132
	s_nop 1
	v_permlane32_swap_b32_e32 v12, v5
	v_lshlrev_b32_e32 v9, 16, v12
	v_and_b32_e32 v12, 0xffff0000, v12
	v_mov_b32_e32 v7, v135
	v_mul_f32_e32 v14, 0xbfb8aa3b, v9
	v_mul_f32_e32 v15, 0xbfb8aa3b, v12
	v_exp_f32_e32 v14, v14
	v_exp_f32_e32 v15, v15
	v_mov_b32_e32 v13, v133
	s_nop 1
	v_permlane32_swap_b32_e32 v13, v7
	v_pk_mul_f32 v[2:3], v[48:49], v[6:7] op_sel_hi:[1,0]
	v_pk_add_f32 v[14:15], v[14:15], 1.0 op_sel_hi:[1,0]
	v_pk_fma_f32 v[2:3], v[4:5], v[32:33], v[2:3] op_sel_hi:[0,1,1]
	v_div_scale_f32 v16, s[0:1], v15, v15, v12
	v_rcp_f32_e32 v17, v16
	v_pk_fma_f32 v[2:3], v[64:65], v[8:9], v[2:3] op_sel_hi:[1,0,1]
	v_fma_f32 v18, -v16, v17, 1.0
	v_fmac_f32_e32 v17, v18, v17
	v_div_scale_f32 v18, vcc, v12, v15, v12
	v_mul_f32_e32 v19, v18, v17
	v_fma_f32 v20, -v16, v19, v18
	v_fmac_f32_e32 v19, v20, v17
	v_fma_f32 v16, -v16, v19, v18
	v_div_fmas_f32 v16, v16, v17, v19
	v_div_fixup_f32 v15, v16, v15, v12
	v_div_scale_f32 v12, s[0:1], v14, v14, v9
	v_rcp_f32_e32 v16, v12
	s_nop 0
	v_fma_f32 v17, -v12, v16, 1.0
	v_fmac_f32_e32 v16, v17, v16
	v_div_scale_f32 v17, vcc, v9, v14, v9
	v_mul_f32_e32 v18, v17, v16
	v_fma_f32 v19, -v12, v18, v17
	v_fmac_f32_e32 v18, v19, v16
	v_fma_f32 v12, -v12, v18, v17
	v_div_fmas_f32 v12, v12, v16, v18
	v_div_fixup_f32 v14, v12, v14, v9
	v_lshlrev_b32_e32 v9, 16, v13
	v_and_b32_e32 v16, 0xffff0000, v13
	v_pk_mul_f32 v[2:3], v[2:3], v[14:15]
	v_mul_f32_e32 v14, 0xbfb8aa3b, v9
	v_mul_f32_e32 v15, 0xbfb8aa3b, v16
	v_exp_f32_e32 v14, v14
	v_exp_f32_e32 v15, v15
	v_pk_mul_f32 v[12:13], v[50:51], v[6:7] op_sel_hi:[1,0]
	v_pk_add_f32 v[14:15], v[14:15], 1.0 op_sel_hi:[1,0]
	s_nop 0
	v_div_scale_f32 v17, s[0:1], v15, v15, v16
	v_rcp_f32_e32 v18, v17
	v_pk_fma_f32 v[12:13], v[4:5], v[34:35], v[12:13] op_sel_hi:[0,1,1]
	v_pk_fma_f32 v[12:13], v[66:67], v[8:9], v[12:13] op_sel_hi:[1,0,1]
	v_fma_f32 v19, -v17, v18, 1.0
	v_fmac_f32_e32 v18, v19, v18
	v_div_scale_f32 v19, vcc, v16, v15, v16
	v_mul_f32_e32 v20, v19, v18
	v_fma_f32 v21, -v17, v20, v19
	v_fmac_f32_e32 v20, v21, v18
	v_fma_f32 v17, -v17, v20, v19
	v_div_fmas_f32 v17, v17, v18, v20
	v_div_fixup_f32 v15, v17, v15, v16
	v_div_scale_f32 v16, s[0:1], v14, v14, v9
	v_rcp_f32_e32 v17, v16
	s_nop 0
	v_fma_f32 v18, -v16, v17, 1.0
	v_fmac_f32_e32 v17, v18, v17
	v_div_scale_f32 v18, vcc, v9, v14, v9
	v_mul_f32_e32 v19, v18, v17
	v_fma_f32 v20, -v16, v19, v18
	v_fmac_f32_e32 v19, v20, v17
	v_fma_f32 v16, -v16, v19, v18
	v_div_fmas_f32 v16, v16, v17, v19
	v_div_fixup_f32 v14, v16, v14, v9
	v_lshlrev_b32_e32 v9, 16, v5
	v_and_b32_e32 v5, 0xffff0000, v5
	v_mul_f32_e32 v16, 0xbfb8aa3b, v9
	v_mul_f32_e32 v17, 0xbfb8aa3b, v5
	v_exp_f32_e32 v16, v16
	v_exp_f32_e32 v17, v17
	v_pk_mul_f32 v[14:15], v[12:13], v[14:15]
	v_pk_mul_f32 v[12:13], v[52:53], v[6:7] op_sel_hi:[1,0]
	v_pk_add_f32 v[16:17], v[16:17], 1.0 op_sel_hi:[1,0]
	s_nop 0
	v_div_scale_f32 v18, s[0:1], v17, v17, v5
	v_rcp_f32_e32 v19, v18
	v_pk_fma_f32 v[12:13], v[4:5], v[36:37], v[12:13] op_sel_hi:[0,1,1]
	v_pk_fma_f32 v[12:13], v[68:69], v[8:9], v[12:13] op_sel_hi:[1,0,1]
	v_fma_f32 v20, -v18, v19, 1.0
	v_fmac_f32_e32 v19, v20, v19
	v_div_scale_f32 v20, vcc, v5, v17, v5
	v_mul_f32_e32 v21, v20, v19
	v_fma_f32 v22, -v18, v21, v20
	v_fmac_f32_e32 v21, v22, v19
	v_fma_f32 v18, -v18, v21, v20
	v_div_fmas_f32 v18, v18, v19, v21
	v_div_fixup_f32 v17, v18, v17, v5
	v_div_scale_f32 v5, s[0:1], v16, v16, v9
	v_rcp_f32_e32 v18, v5
	s_nop 0
	v_fma_f32 v19, -v5, v18, 1.0
	v_fmac_f32_e32 v18, v19, v18
	v_div_scale_f32 v19, vcc, v9, v16, v9
	v_mul_f32_e32 v20, v19, v18
	v_fma_f32 v21, -v5, v20, v19
	v_fmac_f32_e32 v20, v21, v18
	v_fma_f32 v5, -v5, v20, v19
	v_div_fmas_f32 v5, v5, v18, v20
	v_div_fixup_f32 v16, v5, v16, v9
	v_lshlrev_b32_e32 v5, 16, v7
	v_and_b32_e32 v7, 0xffff0000, v7
	v_pk_mul_f32 v[16:17], v[12:13], v[16:17]
	v_pk_mul_f32 v[12:13], v[54:55], v[6:7] op_sel_hi:[1,0]
	s_nop 0
	v_pk_fma_f32 v[12:13], v[4:5], v[38:39], v[12:13] op_sel_hi:[0,1,1]
	v_pk_fma_f32 v[12:13], v[70:71], v[8:9], v[12:13] op_sel_hi:[1,0,1]
	v_mul_f32_e32 v9, 0xbfb8aa3b, v5
	v_exp_f32_e32 v18, v9
	v_mul_f32_e32 v9, 0xbfb8aa3b, v7
	v_exp_f32_e32 v19, v9
	s_nop 0
	v_pk_add_f32 v[18:19], v[18:19], 1.0 op_sel_hi:[1,0]
	s_nop 0
	v_div_scale_f32 v9, s[0:1], v19, v19, v7
	v_rcp_f32_e32 v20, v9
	s_nop 0
	v_fma_f32 v21, -v9, v20, 1.0
	v_fmac_f32_e32 v20, v21, v20
	v_div_scale_f32 v21, vcc, v7, v19, v7
	v_mul_f32_e32 v22, v21, v20
	v_fma_f32 v23, -v9, v22, v21
	v_fmac_f32_e32 v22, v23, v20
	v_fma_f32 v9, -v9, v22, v21
	v_div_fmas_f32 v9, v9, v20, v22
	v_div_fixup_f32 v19, v9, v19, v7
	v_div_scale_f32 v7, s[0:1], v18, v18, v5
	v_rcp_f32_e32 v9, v7
	s_nop 0
	v_fma_f32 v20, -v7, v9, 1.0
	v_fmac_f32_e32 v9, v20, v9
	v_div_scale_f32 v20, vcc, v5, v18, v5
	v_mul_f32_e32 v21, v20, v9
	v_fma_f32 v22, -v7, v21, v20
	v_fmac_f32_e32 v21, v22, v9
	v_fma_f32 v7, -v7, v21, v20
	v_div_fmas_f32 v7, v7, v9, v21
	v_div_fixup_f32 v18, v7, v18, v5
	v_pk_mul_f32 v[18:19], v[12:13], v[18:19]
	v_cvt_pk_bf16_f32 v12, v2, v3
	v_cvt_pk_bf16_f32 v13, v14, v15
	v_cvt_pk_bf16_f32 v14, v16, v17
	v_cvt_pk_bf16_f32 v15, v18, v19
	s_nop 0
	v_permlane32_swap_b32_e32 v12, v14
	v_permlane32_swap_b32_e32 v13, v15
	global_store_dwordx4 v[10:11], v[12:15], off offset:64
	s_waitcnt vmcnt(3)
	v_mov_b32_e32 v5, v138
	s_nop 1
	v_mov_b32_e32 v0, v136
	s_nop 1
	v_permlane32_swap_b32_e32 v0, v5
	v_lshlrev_b32_e32 v9, 16, v0
	v_and_b32_e32 v0, 0xffff0000, v0
	v_mul_f32_e32 v12, 0xbfb8aa3b, v9
	v_mul_f32_e32 v13, 0xbfb8aa3b, v0
	v_exp_f32_e32 v12, v12
	v_exp_f32_e32 v13, v13
	v_mov_b32_e32 v7, v139
	s_nop 1
	v_mov_b32_e32 v1, v137
	s_nop 1
	v_permlane32_swap_b32_e32 v1, v7
	v_pk_add_f32 v[12:13], v[12:13], 1.0 op_sel_hi:[1,0]
	v_pk_mul_f32 v[2:3], v[56:57], v[6:7] op_sel_hi:[1,0]
	v_div_scale_f32 v14, s[0:1], v13, v13, v0
	v_rcp_f32_e32 v15, v14
	v_pk_fma_f32 v[2:3], v[4:5], v[40:41], v[2:3] op_sel_hi:[0,1,1]
	v_pk_fma_f32 v[2:3], v[72:73], v[8:9], v[2:3] op_sel_hi:[1,0,1]
	v_fma_f32 v16, -v14, v15, 1.0
	v_fmac_f32_e32 v15, v16, v15
	v_div_scale_f32 v16, vcc, v0, v13, v0
	v_mul_f32_e32 v17, v16, v15
	v_fma_f32 v18, -v14, v17, v16
	v_fmac_f32_e32 v17, v18, v15
	v_fma_f32 v14, -v14, v17, v16
	v_div_fmas_f32 v14, v14, v15, v17
	v_div_fixup_f32 v13, v14, v13, v0
	v_div_scale_f32 v0, s[0:1], v12, v12, v9
	v_rcp_f32_e32 v14, v0
	s_nop 0
	v_fma_f32 v15, -v0, v14, 1.0
	v_fmac_f32_e32 v14, v15, v14
	v_div_scale_f32 v15, vcc, v9, v12, v9
	v_mul_f32_e32 v16, v15, v14
	v_fma_f32 v17, -v0, v16, v15
	v_fmac_f32_e32 v16, v17, v14
	v_fma_f32 v0, -v0, v16, v15
	v_div_fmas_f32 v0, v0, v14, v16
	v_div_fixup_f32 v12, v0, v12, v9
	v_lshlrev_b32_e32 v9, 16, v1
	v_and_b32_e32 v14, 0xffff0000, v1
	v_pk_mul_f32 v[2:3], v[2:3], v[12:13]
	v_mul_f32_e32 v12, 0xbfb8aa3b, v9
	v_mul_f32_e32 v13, 0xbfb8aa3b, v14
	v_exp_f32_e32 v12, v12
	v_exp_f32_e32 v13, v13
	v_pk_mul_f32 v[0:1], v[58:59], v[6:7] op_sel_hi:[1,0]
	v_cvt_pk_bf16_f32 v2, v2, v3
	v_pk_fma_f32 v[0:1], v[4:5], v[42:43], v[0:1] op_sel_hi:[0,1,1]
	v_pk_add_f32 v[12:13], v[12:13], 1.0 op_sel_hi:[1,0]
	v_pk_fma_f32 v[0:1], v[74:75], v[8:9], v[0:1] op_sel_hi:[1,0,1]
	v_div_scale_f32 v15, s[0:1], v13, v13, v14
	v_rcp_f32_e32 v16, v15
	s_nop 0
	v_fma_f32 v17, -v15, v16, 1.0
	v_fmac_f32_e32 v16, v17, v16
	v_div_scale_f32 v17, vcc, v14, v13, v14
	v_mul_f32_e32 v18, v17, v16
	v_fma_f32 v19, -v15, v18, v17
	v_fmac_f32_e32 v18, v19, v16
	v_fma_f32 v15, -v15, v18, v17
	v_div_fmas_f32 v15, v15, v16, v18
	v_div_fixup_f32 v13, v15, v13, v14
	v_div_scale_f32 v14, s[0:1], v12, v12, v9
	v_rcp_f32_e32 v15, v14
	s_nop 0
	v_fma_f32 v16, -v14, v15, 1.0
	v_fmac_f32_e32 v15, v16, v15
	v_div_scale_f32 v16, vcc, v9, v12, v9
	v_mul_f32_e32 v17, v16, v15
	v_fma_f32 v18, -v14, v17, v16
	v_fmac_f32_e32 v17, v18, v15
	v_fma_f32 v14, -v14, v17, v16
	v_div_fmas_f32 v14, v14, v15, v17
	v_div_fixup_f32 v12, v14, v12, v9
	v_lshlrev_b32_e32 v9, 16, v5
	v_and_b32_e32 v5, 0xffff0000, v5
	v_mul_f32_e32 v14, 0xbfb8aa3b, v9
	v_mul_f32_e32 v15, 0xbfb8aa3b, v5
	v_exp_f32_e32 v14, v14
	v_exp_f32_e32 v15, v15
	v_pk_mul_f32 v[0:1], v[0:1], v[12:13]
	v_pk_mul_f32 v[12:13], v[60:61], v[6:7] op_sel_hi:[1,0]
	v_cvt_pk_bf16_f32 v3, v0, v1
	v_pk_add_f32 v[14:15], v[14:15], 1.0 op_sel_hi:[1,0]
	v_pk_fma_f32 v[12:13], v[4:5], v[44:45], v[12:13] op_sel_hi:[0,1,1]
	v_div_scale_f32 v16, s[0:1], v15, v15, v5
	v_rcp_f32_e32 v17, v16
	v_pk_fma_f32 v[12:13], v[76:77], v[8:9], v[12:13] op_sel_hi:[1,0,1]
	v_fma_f32 v18, -v16, v17, 1.0
	v_fmac_f32_e32 v17, v18, v17
	v_div_scale_f32 v18, vcc, v5, v15, v5
	v_mul_f32_e32 v19, v18, v17
	v_fma_f32 v20, -v16, v19, v18
	v_fmac_f32_e32 v19, v20, v17
	v_fma_f32 v16, -v16, v19, v18
	v_div_fmas_f32 v16, v16, v17, v19
	v_div_fixup_f32 v15, v16, v15, v5
	v_div_scale_f32 v5, s[0:1], v14, v14, v9
	v_rcp_f32_e32 v16, v5
	s_nop 0
	v_fma_f32 v17, -v5, v16, 1.0
	v_fmac_f32_e32 v16, v17, v16
	v_div_scale_f32 v17, vcc, v9, v14, v9
	v_mul_f32_e32 v18, v17, v16
	v_fma_f32 v19, -v5, v18, v17
	v_fmac_f32_e32 v18, v19, v16
	v_fma_f32 v5, -v5, v18, v17
	v_div_fmas_f32 v5, v5, v16, v18
	v_div_fixup_f32 v14, v5, v14, v9
	v_pk_mul_f32 v[12:13], v[12:13], v[14:15]
	v_lshlrev_b32_e32 v9, 16, v7
	v_and_b32_e32 v14, 0xffff0000, v7
	v_pk_mul_f32 v[6:7], v[62:63], v[6:7] op_sel_hi:[1,0]
	s_nop 0
	v_pk_fma_f32 v[4:5], v[4:5], v[46:47], v[6:7] op_sel_hi:[0,1,1]
	v_mul_f32_e32 v6, 0xbfb8aa3b, v9
	v_mul_f32_e32 v7, 0xbfb8aa3b, v14
	v_exp_f32_e32 v6, v6
	v_exp_f32_e32 v7, v7
	v_pk_fma_f32 v[4:5], v[78:79], v[8:9], v[4:5] op_sel_hi:[1,0,1]
	v_pk_add_f32 v[6:7], v[6:7], 1.0 op_sel_hi:[1,0]
	s_nop 0
	v_div_scale_f32 v8, s[0:1], v7, v7, v14
	v_rcp_f32_e32 v15, v8
	s_nop 0
	v_fma_f32 v16, -v8, v15, 1.0
	v_fmac_f32_e32 v15, v16, v15
	v_div_scale_f32 v16, vcc, v14, v7, v14
	v_mul_f32_e32 v17, v16, v15
	v_fma_f32 v18, -v8, v17, v16
	v_fmac_f32_e32 v17, v18, v15
	v_fma_f32 v8, -v8, v17, v16
	v_div_fmas_f32 v8, v8, v15, v17
	v_div_fixup_f32 v7, v8, v7, v14
	v_div_scale_f32 v8, s[0:1], v6, v6, v9
	v_rcp_f32_e32 v14, v8
	s_nop 0
	v_fma_f32 v15, -v8, v14, 1.0
	v_fmac_f32_e32 v14, v15, v14
	v_div_scale_f32 v15, vcc, v9, v6, v9
	v_mul_f32_e32 v16, v15, v14
	v_fma_f32 v17, -v8, v16, v15
	v_fmac_f32_e32 v16, v17, v14
	v_fma_f32 v8, -v8, v16, v15
	v_div_fmas_f32 v8, v8, v14, v16
	v_div_fixup_f32 v6, v8, v6, v9
	v_pk_mul_f32 v[6:7], v[4:5], v[6:7]
	v_cvt_pk_bf16_f32 v4, v12, v13
	v_cvt_pk_bf16_f32 v5, v6, v7
	s_nop 0
	v_permlane32_swap_b32_e32 v2, v4
	v_permlane32_swap_b32_e32 v3, v5
	global_store_dwordx4 v[10:11], v[2:5], off offset:96

.LBB0_513:
	s_mov_b64 s[8:9], 0x3e38aa3b
	s_lshl_b32 s0, s1, 1
	s_mov_b32 s1, s9
	v_readlane_b32 s8, v254, 43
	v_lshlrev_b64 v[2:3], 11, v[130:131]
	v_readlane_b32 s9, v254, 44
	v_lshl_add_u64 v[0:1], v[132:133], 0, s[0:1]
	v_mov_b32_e32 v129, v193
	v_lshl_add_u64 v[2:3], s[8:9], 0, v[2:3]
	v_lshl_add_u64 v[2:3], v[2:3], 0, s[0:1]
	v_lshl_add_u64 v[6:7], v[0:1], 0, v[128:129]
	s_mov_b64 s[0:1], 0x1a00
	v_lshl_add_u64 v[0:1], v[6:7], 0, s[0:1]
	v_add_co_u32_e32 v6, vcc, 0x1000, v6
	v_lshl_add_u64 v[2:3], v[2:3], 0, v[128:129]
	s_nop 0
	v_addc_co_u32_e32 v7, vcc, 0, v7, vcc
	v_readlane_b32 s98, v253, 59
	v_readlane_b32 s99, v253, 60
	s_nop 1
	v_writelane_b32 v76, s98, 40
	v_writelane_b32 v77, s99, 40
	s_mov_b64 s[98:99], exec
	v_cmpx_eq_u32_e64 exec, 40, v234
	s_nop 3
	v_writelane_b32 v255, exec_hi, 41
	global_atomic_add v255, v[76:77], v251, off sc0
	s_mov_b64 exec, s[98:99]
	global_load_dwordx4 v[6:9], v[6:7], off offset:2560
	global_load_dwordx4 v[64:67], v[0:1], off offset:32
	global_load_dwordx4 v[68:71], v[0:1], off offset:64
	global_load_dwordx4 v[72:75], v[0:1], off offset:96
	s_mov_b64 s[0:1], 0xd210600
	v_lshl_add_u64 v[4:5], v[2:3], 0, s[0:1]
	v_readlane_b32 s76, v254, 37
	v_readlane_b32 s77, v254, 38
	s_mov_b64 s[8:9], 0
	s_waitcnt vmcnt(3) lgkmcnt(0)
	v_mov_b32_e32 v12, v8
	s_nop 1
	v_permlane32_swap_b32_e32 v6, v12
	v_lshlrev_b32_e32 v10, 16, v6
	v_and_b32_e32 v6, 0xffff0000, v6
	v_mov_b32_e32 v14, v9
	v_mul_f32_e32 v8, 0xbfb8aa3b, v10
	v_mul_f32_e32 v9, 0xbfb8aa3b, v6
	v_exp_f32_e32 v8, v8
	v_exp_f32_e32 v9, v9
	v_permlane32_swap_b32_e32 v7, v14
	v_pk_add_f32 v[8:9], v[8:9], 1.0 op_sel_hi:[1,0]
	s_nop 0
	v_div_scale_f32 v11, s[0:1], v9, v9, v6
	v_rcp_f32_e32 v13, v11
	s_nop 0
	v_fma_f32 v15, -v11, v13, 1.0
	v_fmac_f32_e32 v13, v15, v13
	v_div_scale_f32 v15, vcc, v6, v9, v6
	v_mul_f32_e32 v16, v15, v13
	v_fma_f32 v17, -v11, v16, v15
	v_fmac_f32_e32 v16, v17, v13
	v_fma_f32 v11, -v11, v16, v15
	v_div_fmas_f32 v11, v11, v13, v16
	v_div_fixup_f32 v9, v11, v9, v6
	v_div_scale_f32 v6, s[0:1], v8, v8, v10
	v_rcp_f32_e32 v11, v6
	s_nop 0
	v_fma_f32 v13, -v6, v11, 1.0
	v_fmac_f32_e32 v11, v13, v11
	v_div_scale_f32 v13, vcc, v10, v8, v10
	v_mul_f32_e32 v15, v13, v11
	v_fma_f32 v16, -v6, v15, v13
	v_fmac_f32_e32 v15, v16, v11
	v_fma_f32 v6, -v6, v15, v13
	v_div_fmas_f32 v6, v6, v11, v15
	v_div_fixup_f32 v8, v6, v8, v10
	v_lshlrev_b32_e32 v10, 16, v7
	v_and_b32_e32 v11, 0xffff0000, v7
	v_mul_f32_e32 v6, 0xbfb8aa3b, v10
	v_mul_f32_e32 v7, 0xbfb8aa3b, v11
	v_exp_f32_e32 v6, v6
	v_exp_f32_e32 v7, v7
	v_pk_mul_f32 v[8:9], v[48:49], v[8:9]
	v_pk_add_f32 v[6:7], v[6:7], 1.0 op_sel_hi:[1,0]
	s_nop 0
	v_div_scale_f32 v13, s[0:1], v7, v7, v11
	v_rcp_f32_e32 v15, v13
	s_nop 0
	v_fma_f32 v16, -v13, v15, 1.0
	v_fmac_f32_e32 v15, v16, v15
	v_div_scale_f32 v16, vcc, v11, v7, v11
	v_mul_f32_e32 v17, v16, v15
	v_fma_f32 v18, -v13, v17, v16
	v_fmac_f32_e32 v17, v18, v15
	v_fma_f32 v13, -v13, v17, v16
	v_div_fmas_f32 v13, v13, v15, v17
	v_div_fixup_f32 v7, v13, v7, v11
	v_div_scale_f32 v11, s[0:1], v6, v6, v10
	v_rcp_f32_e32 v13, v11
	s_nop 0
	v_fma_f32 v15, -v11, v13, 1.0
	v_fmac_f32_e32 v13, v15, v13
	v_div_scale_f32 v15, vcc, v10, v6, v10
	v_mul_f32_e32 v16, v15, v13
	v_fma_f32 v17, -v11, v16, v15
	v_fmac_f32_e32 v16, v17, v13
	v_fma_f32 v11, -v11, v16, v15
	v_div_fmas_f32 v11, v11, v13, v16
	v_div_fixup_f32 v6, v11, v6, v10
	v_lshlrev_b32_e32 v13, 16, v12
	v_and_b32_e32 v12, 0xffff0000, v12
	v_pk_mul_f32 v[10:11], v[50:51], v[6:7]
	v_mul_f32_e32 v6, 0xbfb8aa3b, v13
	v_mul_f32_e32 v7, 0xbfb8aa3b, v12
	v_exp_f32_e32 v6, v6
	v_exp_f32_e32 v7, v7
	s_nop 0
	v_pk_add_f32 v[6:7], v[6:7], 1.0 op_sel_hi:[1,0]
	s_nop 0
	v_div_scale_f32 v15, s[0:1], v7, v7, v12
	v_rcp_f32_e32 v16, v15
	s_nop 0
	v_fma_f32 v17, -v15, v16, 1.0
	v_fmac_f32_e32 v16, v17, v16
	v_div_scale_f32 v17, vcc, v12, v7, v12
	v_mul_f32_e32 v18, v17, v16
	v_fma_f32 v19, -v15, v18, v17
	v_fmac_f32_e32 v18, v19, v16
	v_fma_f32 v15, -v15, v18, v17
	v_div_fmas_f32 v15, v15, v16, v18
	v_div_fixup_f32 v7, v15, v7, v12
	v_div_scale_f32 v12, s[0:1], v6, v6, v13
	v_rcp_f32_e32 v15, v12
	s_nop 0
	v_fma_f32 v16, -v12, v15, 1.0
	v_fmac_f32_e32 v15, v16, v15
	v_div_scale_f32 v16, vcc, v13, v6, v13
	v_mul_f32_e32 v17, v16, v15
	v_fma_f32 v18, -v12, v17, v16
	v_fmac_f32_e32 v17, v18, v15
	v_fma_f32 v12, -v12, v17, v16
	v_div_fmas_f32 v12, v12, v15, v17
	v_div_fixup_f32 v6, v12, v6, v13
	v_lshlrev_b32_e32 v15, 16, v14
	v_and_b32_e32 v14, 0xffff0000, v14
	v_pk_mul_f32 v[12:13], v[52:53], v[6:7]
	v_mul_f32_e32 v6, 0xbfb8aa3b, v15
	v_mul_f32_e32 v7, 0xbfb8aa3b, v14
	v_exp_f32_e32 v6, v6
	v_exp_f32_e32 v7, v7
	s_nop 0
	v_pk_add_f32 v[6:7], v[6:7], 1.0 op_sel_hi:[1,0]
	s_nop 0
	v_div_scale_f32 v16, s[0:1], v7, v7, v14
	v_rcp_f32_e32 v17, v16
	s_nop 0
	v_fma_f32 v18, -v16, v17, 1.0
	v_fmac_f32_e32 v17, v18, v17
	v_div_scale_f32 v18, vcc, v14, v7, v14
	v_mul_f32_e32 v19, v18, v17
	v_fma_f32 v20, -v16, v19, v18
	v_fmac_f32_e32 v19, v20, v17
	v_fma_f32 v16, -v16, v19, v18
	v_div_fmas_f32 v16, v16, v17, v19
	v_div_fixup_f32 v7, v16, v7, v14
	v_div_scale_f32 v14, s[0:1], v6, v6, v15
	v_rcp_f32_e32 v16, v14
	s_mov_b32 s0, 0xd210000
	v_fma_f32 v17, -v14, v16, 1.0
	v_fmac_f32_e32 v16, v17, v16
	v_div_scale_f32 v17, vcc, v15, v6, v15
	v_mul_f32_e32 v18, v17, v16
	v_fma_f32 v19, -v14, v18, v17
	v_fmac_f32_e32 v18, v19, v16
	v_fma_f32 v14, -v14, v18, v17
	v_div_fmas_f32 v14, v14, v16, v18
	v_div_fixup_f32 v6, v14, v6, v15
	v_pk_mul_f32 v[14:15], v[54:55], v[6:7]
	v_cvt_pk_bf16_f32 v6, v8, v9
	v_cvt_pk_bf16_f32 v7, v10, v11
	v_cvt_pk_bf16_f32 v8, v12, v13
	v_cvt_pk_bf16_f32 v9, v14, v15
	v_add_co_u32_e32 v2, vcc, s0, v2
	v_permlane32_swap_b32_e32 v6, v8
	v_permlane32_swap_b32_e32 v7, v9
	v_addc_co_u32_e32 v3, vcc, 0, v3, vcc
	global_store_dwordx4 v[2:3], v[6:9], off offset:1536
	s_waitcnt vmcnt(3)
	v_mov_b32_e32 v10, v66
	s_nop 1
	v_mov_b32_e32 v6, v64
	s_nop 1
	v_permlane32_swap_b32_e32 v6, v10
	v_lshlrev_b32_e32 v8, 16, v6
	v_and_b32_e32 v6, 0xffff0000, v6
	v_mul_f32_e32 v2, 0xbfb8aa3b, v8
	v_mul_f32_e32 v3, 0xbfb8aa3b, v6
	v_exp_f32_e32 v2, v2
	v_exp_f32_e32 v3, v3
	v_mov_b32_e32 v12, v67
	s_nop 1
	v_mov_b32_e32 v7, v65
	s_nop 1
	v_permlane32_swap_b32_e32 v7, v12
	v_pk_add_f32 v[2:3], v[2:3], 1.0 op_sel_hi:[1,0]
	s_nop 0
	v_div_scale_f32 v9, s[0:1], v3, v3, v6
	v_rcp_f32_e32 v11, v9
	s_nop 0
	v_fma_f32 v13, -v9, v11, 1.0
	v_fmac_f32_e32 v11, v13, v11
	v_div_scale_f32 v13, vcc, v6, v3, v6
	v_mul_f32_e32 v14, v13, v11
	v_fma_f32 v15, -v9, v14, v13
	v_fmac_f32_e32 v14, v15, v11
	v_fma_f32 v9, -v9, v14, v13
	v_div_fmas_f32 v9, v9, v11, v14
	v_div_fixup_f32 v3, v9, v3, v6
	v_div_scale_f32 v6, s[0:1], v2, v2, v8
	v_rcp_f32_e32 v9, v6
	s_nop 0
	v_fma_f32 v11, -v6, v9, 1.0
	v_fmac_f32_e32 v9, v11, v9
	v_div_scale_f32 v11, vcc, v8, v2, v8
	v_mul_f32_e32 v13, v11, v9
	v_fma_f32 v14, -v6, v13, v11
	v_fmac_f32_e32 v13, v14, v9
	v_fma_f32 v6, -v6, v13, v11
	v_div_fmas_f32 v6, v6, v9, v13
	v_div_fixup_f32 v2, v6, v2, v8
	v_lshlrev_b32_e32 v8, 16, v7
	v_and_b32_e32 v9, 0xffff0000, v7
	v_mul_f32_e32 v6, 0xbfb8aa3b, v8
	v_mul_f32_e32 v7, 0xbfb8aa3b, v9
	v_exp_f32_e32 v6, v6
	v_exp_f32_e32 v7, v7
	v_pk_mul_f32 v[2:3], v[56:57], v[2:3]
	v_pk_add_f32 v[6:7], v[6:7], 1.0 op_sel_hi:[1,0]
	s_nop 0
	v_div_scale_f32 v11, s[0:1], v7, v7, v9
	v_rcp_f32_e32 v13, v11
	s_nop 0
	v_fma_f32 v14, -v11, v13, 1.0
	v_fmac_f32_e32 v13, v14, v13
	v_div_scale_f32 v14, vcc, v9, v7, v9
	v_mul_f32_e32 v15, v14, v13
	v_fma_f32 v16, -v11, v15, v14
	v_fmac_f32_e32 v15, v16, v13
	v_fma_f32 v11, -v11, v15, v14
	v_div_fmas_f32 v11, v11, v13, v15
	v_div_fixup_f32 v7, v11, v7, v9
	v_div_scale_f32 v9, s[0:1], v6, v6, v8
	v_rcp_f32_e32 v11, v9
	s_nop 0
	v_fma_f32 v13, -v9, v11, 1.0
	v_fmac_f32_e32 v11, v13, v11
	v_div_scale_f32 v13, vcc, v8, v6, v8
	v_mul_f32_e32 v14, v13, v11
	v_fma_f32 v15, -v9, v14, v13
	v_fmac_f32_e32 v14, v15, v11
	v_fma_f32 v9, -v9, v14, v13
	v_div_fmas_f32 v9, v9, v11, v14
	v_div_fixup_f32 v6, v9, v6, v8
	v_lshlrev_b32_e32 v11, 16, v10
	v_and_b32_e32 v10, 0xffff0000, v10
	v_pk_mul_f32 v[8:9], v[58:59], v[6:7]
	v_mul_f32_e32 v6, 0xbfb8aa3b, v11
	v_mul_f32_e32 v7, 0xbfb8aa3b, v10
	v_exp_f32_e32 v6, v6
	v_exp_f32_e32 v7, v7
	s_nop 0
	v_pk_add_f32 v[6:7], v[6:7], 1.0 op_sel_hi:[1,0]
	s_nop 0
	v_div_scale_f32 v13, s[0:1], v7, v7, v10
	v_rcp_f32_e32 v14, v13
	s_nop 0
	v_fma_f32 v15, -v13, v14, 1.0
	v_fmac_f32_e32 v14, v15, v14
	v_div_scale_f32 v15, vcc, v10, v7, v10
	v_mul_f32_e32 v16, v15, v14
	v_fma_f32 v17, -v13, v16, v15
	v_fmac_f32_e32 v16, v17, v14
	v_fma_f32 v13, -v13, v16, v15
	v_div_fmas_f32 v13, v13, v14, v16
	v_div_fixup_f32 v7, v13, v7, v10
	v_div_scale_f32 v10, s[0:1], v6, v6, v11
	v_rcp_f32_e32 v13, v10
	s_nop 0
	v_fma_f32 v14, -v10, v13, 1.0
	v_fmac_f32_e32 v13, v14, v13
	v_div_scale_f32 v14, vcc, v11, v6, v11
	v_mul_f32_e32 v15, v14, v13
	v_fma_f32 v16, -v10, v15, v14
	v_fmac_f32_e32 v15, v16, v13
	v_fma_f32 v10, -v10, v15, v14
	v_div_fmas_f32 v10, v10, v13, v15
	v_div_fixup_f32 v6, v10, v6, v11
	v_lshlrev_b32_e32 v13, 16, v12
	v_and_b32_e32 v12, 0xffff0000, v12
	v_pk_mul_f32 v[10:11], v[60:61], v[6:7]
	v_mul_f32_e32 v6, 0xbfb8aa3b, v13
	v_mul_f32_e32 v7, 0xbfb8aa3b, v12
	v_exp_f32_e32 v6, v6
	v_exp_f32_e32 v7, v7
	s_nop 0
	v_pk_add_f32 v[6:7], v[6:7], 1.0 op_sel_hi:[1,0]
	s_nop 0
	v_div_scale_f32 v14, s[0:1], v7, v7, v12
	v_rcp_f32_e32 v15, v14
	s_nop 0
	v_fma_f32 v16, -v14, v15, 1.0
	v_fmac_f32_e32 v15, v16, v15
	v_div_scale_f32 v16, vcc, v12, v7, v12
	v_mul_f32_e32 v17, v16, v15
	v_fma_f32 v18, -v14, v17, v16
	v_fmac_f32_e32 v17, v18, v15
	v_fma_f32 v14, -v14, v17, v16
	v_div_fmas_f32 v14, v14, v15, v17
	v_div_fixup_f32 v7, v14, v7, v12
	v_div_scale_f32 v12, s[0:1], v6, v6, v13
	v_rcp_f32_e32 v14, v12
	s_nop 0
	v_fma_f32 v15, -v12, v14, 1.0
	v_fmac_f32_e32 v14, v15, v14
	v_div_scale_f32 v15, vcc, v13, v6, v13
	v_mul_f32_e32 v16, v15, v14
	v_fma_f32 v17, -v12, v16, v15
	v_fmac_f32_e32 v16, v17, v14
	v_fma_f32 v12, -v12, v16, v15
	v_div_fmas_f32 v12, v12, v14, v16
	v_div_fixup_f32 v6, v12, v6, v13
	v_pk_mul_f32 v[12:13], v[62:63], v[6:7]
	v_cvt_pk_bf16_f32 v6, v2, v3
	v_cvt_pk_bf16_f32 v7, v8, v9
	v_cvt_pk_bf16_f32 v8, v10, v11
	v_cvt_pk_bf16_f32 v9, v12, v13
	s_nop 0
	v_permlane32_swap_b32_e32 v6, v8
	v_permlane32_swap_b32_e32 v7, v9
	global_store_dwordx4 v[4:5], v[6:9], off offset:32
	s_waitcnt vmcnt(3)
	v_mov_b32_e32 v10, v70
	s_nop 1
	v_mov_b32_e32 v6, v68
	s_nop 1
	v_permlane32_swap_b32_e32 v6, v10
	v_lshlrev_b32_e32 v8, 16, v6
	v_and_b32_e32 v6, 0xffff0000, v6
	v_mul_f32_e32 v2, 0xbfb8aa3b, v8
	v_mul_f32_e32 v3, 0xbfb8aa3b, v6
	v_exp_f32_e32 v2, v2
	v_exp_f32_e32 v3, v3
	v_mov_b32_e32 v12, v71
	s_nop 1
	v_mov_b32_e32 v7, v69
	s_nop 1
	v_permlane32_swap_b32_e32 v7, v12
	v_pk_add_f32 v[2:3], v[2:3], 1.0 op_sel_hi:[1,0]
	s_nop 0
	v_div_scale_f32 v9, s[0:1], v3, v3, v6
	v_rcp_f32_e32 v11, v9
	s_nop 0
	v_fma_f32 v13, -v9, v11, 1.0
	v_fmac_f32_e32 v11, v13, v11
	v_div_scale_f32 v13, vcc, v6, v3, v6
	v_mul_f32_e32 v14, v13, v11
	v_fma_f32 v15, -v9, v14, v13
	v_fmac_f32_e32 v14, v15, v11
	v_fma_f32 v9, -v9, v14, v13
	v_div_fmas_f32 v9, v9, v11, v14
	v_div_fixup_f32 v3, v9, v3, v6
	v_div_scale_f32 v6, s[0:1], v2, v2, v8
	v_rcp_f32_e32 v9, v6
	s_nop 0
	v_fma_f32 v11, -v6, v9, 1.0
	v_fmac_f32_e32 v9, v11, v9
	v_div_scale_f32 v11, vcc, v8, v2, v8
	v_mul_f32_e32 v13, v11, v9
	v_fma_f32 v14, -v6, v13, v11
	v_fmac_f32_e32 v13, v14, v9
	v_fma_f32 v6, -v6, v13, v11
	v_div_fmas_f32 v6, v6, v9, v13
	v_div_fixup_f32 v2, v6, v2, v8
	v_lshlrev_b32_e32 v8, 16, v7
	v_and_b32_e32 v9, 0xffff0000, v7
	v_mul_f32_e32 v6, 0xbfb8aa3b, v8
	v_mul_f32_e32 v7, 0xbfb8aa3b, v9
	v_exp_f32_e32 v6, v6
	v_exp_f32_e32 v7, v7
	v_pk_mul_f32 v[2:3], v[32:33], v[2:3]
	v_pk_add_f32 v[6:7], v[6:7], 1.0 op_sel_hi:[1,0]
	s_nop 0
	v_div_scale_f32 v11, s[0:1], v7, v7, v9
	v_rcp_f32_e32 v13, v11
	s_nop 0
	v_fma_f32 v14, -v11, v13, 1.0
	v_fmac_f32_e32 v13, v14, v13
	v_div_scale_f32 v14, vcc, v9, v7, v9
	v_mul_f32_e32 v15, v14, v13
	v_fma_f32 v16, -v11, v15, v14
	v_fmac_f32_e32 v15, v16, v13
	v_fma_f32 v11, -v11, v15, v14
	v_div_fmas_f32 v11, v11, v13, v15
	v_div_fixup_f32 v7, v11, v7, v9
	v_div_scale_f32 v9, s[0:1], v6, v6, v8
	v_rcp_f32_e32 v11, v9
	s_nop 0
	v_fma_f32 v13, -v9, v11, 1.0
	v_fmac_f32_e32 v11, v13, v11
	v_div_scale_f32 v13, vcc, v8, v6, v8
	v_mul_f32_e32 v14, v13, v11
	v_fma_f32 v15, -v9, v14, v13
	v_fmac_f32_e32 v14, v15, v11
	v_fma_f32 v9, -v9, v14, v13
	v_div_fmas_f32 v9, v9, v11, v14
	v_div_fixup_f32 v6, v9, v6, v8
	v_lshlrev_b32_e32 v11, 16, v10
	v_and_b32_e32 v10, 0xffff0000, v10
	v_pk_mul_f32 v[8:9], v[34:35], v[6:7]
	v_mul_f32_e32 v6, 0xbfb8aa3b, v11
	v_mul_f32_e32 v7, 0xbfb8aa3b, v10
	v_exp_f32_e32 v6, v6
	v_exp_f32_e32 v7, v7
	s_nop 0
	v_pk_add_f32 v[6:7], v[6:7], 1.0 op_sel_hi:[1,0]
	s_nop 0
	v_div_scale_f32 v13, s[0:1], v7, v7, v10
	v_rcp_f32_e32 v14, v13
	s_nop 0
	v_fma_f32 v15, -v13, v14, 1.0
	v_fmac_f32_e32 v14, v15, v14
	v_div_scale_f32 v15, vcc, v10, v7, v10
	v_mul_f32_e32 v16, v15, v14
	v_fma_f32 v17, -v13, v16, v15
	v_fmac_f32_e32 v16, v17, v14
	v_fma_f32 v13, -v13, v16, v15
	v_div_fmas_f32 v13, v13, v14, v16
	v_div_fixup_f32 v7, v13, v7, v10
	v_div_scale_f32 v10, s[0:1], v6, v6, v11
	v_rcp_f32_e32 v13, v10
	s_nop 0
	v_fma_f32 v14, -v10, v13, 1.0
	v_fmac_f32_e32 v13, v14, v13
	v_div_scale_f32 v14, vcc, v11, v6, v11
	v_mul_f32_e32 v15, v14, v13
	v_fma_f32 v16, -v10, v15, v14
	v_fmac_f32_e32 v15, v16, v13
	v_fma_f32 v10, -v10, v15, v14
	v_div_fmas_f32 v10, v10, v13, v15
	v_div_fixup_f32 v6, v10, v6, v11
	v_lshlrev_b32_e32 v13, 16, v12
	v_and_b32_e32 v12, 0xffff0000, v12
	v_pk_mul_f32 v[10:11], v[36:37], v[6:7]
	v_mul_f32_e32 v6, 0xbfb8aa3b, v13
	v_mul_f32_e32 v7, 0xbfb8aa3b, v12
	v_exp_f32_e32 v6, v6
	v_exp_f32_e32 v7, v7
	s_nop 0
	v_pk_add_f32 v[6:7], v[6:7], 1.0 op_sel_hi:[1,0]
	s_nop 0
	v_div_scale_f32 v14, s[0:1], v7, v7, v12
	v_rcp_f32_e32 v15, v14
	s_nop 0
	v_fma_f32 v16, -v14, v15, 1.0
	v_fmac_f32_e32 v15, v16, v15
	v_div_scale_f32 v16, vcc, v12, v7, v12
	v_mul_f32_e32 v17, v16, v15
	v_fma_f32 v18, -v14, v17, v16
	v_fmac_f32_e32 v17, v18, v15
	v_fma_f32 v14, -v14, v17, v16
	v_div_fmas_f32 v14, v14, v15, v17
	v_div_fixup_f32 v7, v14, v7, v12
	v_div_scale_f32 v12, s[0:1], v6, v6, v13
	v_rcp_f32_e32 v14, v12
	s_nop 0
	v_fma_f32 v15, -v12, v14, 1.0
	v_fmac_f32_e32 v14, v15, v14
	v_div_scale_f32 v15, vcc, v13, v6, v13
	v_mul_f32_e32 v16, v15, v14
	v_fma_f32 v17, -v12, v16, v15
	v_fmac_f32_e32 v16, v17, v14
	v_fma_f32 v12, -v12, v16, v15
	v_div_fmas_f32 v12, v12, v14, v16
	v_div_fixup_f32 v6, v12, v6, v13
	v_pk_mul_f32 v[12:13], v[38:39], v[6:7]
	v_cvt_pk_bf16_f32 v6, v2, v3
	v_cvt_pk_bf16_f32 v7, v8, v9
	v_cvt_pk_bf16_f32 v8, v10, v11
	v_cvt_pk_bf16_f32 v9, v12, v13
	s_nop 0
	v_permlane32_swap_b32_e32 v6, v8
	v_permlane32_swap_b32_e32 v7, v9
	global_store_dwordx4 v[4:5], v[6:9], off offset:64
	s_waitcnt vmcnt(3)
	v_mov_b32_e32 v10, v75
	v_mov_b32_e32 v8, v74
	s_nop 1
	v_mov_b32_e32 v0, v72
	s_nop 1
	v_permlane32_swap_b32_e32 v0, v8
	v_lshlrev_b32_e32 v6, 16, v0
	v_and_b32_e32 v0, 0xffff0000, v0
	v_mul_f32_e32 v2, 0xbfb8aa3b, v6
	v_mul_f32_e32 v3, 0xbfb8aa3b, v0
	v_exp_f32_e32 v2, v2
	v_exp_f32_e32 v3, v3
	v_mov_b32_e32 v1, v73
	s_nop 1
	v_permlane32_swap_b32_e32 v1, v10
	v_pk_add_f32 v[2:3], v[2:3], 1.0 op_sel_hi:[1,0]
	s_nop 0
	v_div_scale_f32 v7, s[0:1], v3, v3, v0
	v_rcp_f32_e32 v9, v7
	s_nop 0
	v_fma_f32 v11, -v7, v9, 1.0
	v_fmac_f32_e32 v9, v11, v9
	v_div_scale_f32 v11, vcc, v0, v3, v0
	v_mul_f32_e32 v12, v11, v9
	v_fma_f32 v13, -v7, v12, v11
	v_fmac_f32_e32 v12, v13, v9
	v_fma_f32 v7, -v7, v12, v11
	v_div_fmas_f32 v7, v7, v9, v12
	v_div_fixup_f32 v3, v7, v3, v0
	v_div_scale_f32 v0, s[0:1], v2, v2, v6
	v_rcp_f32_e32 v7, v0
	s_nop 0
	v_fma_f32 v9, -v0, v7, 1.0
	v_fmac_f32_e32 v7, v9, v7
	v_div_scale_f32 v9, vcc, v6, v2, v6
	v_mul_f32_e32 v11, v9, v7
	v_fma_f32 v12, -v0, v11, v9
	v_fmac_f32_e32 v11, v12, v7
	v_fma_f32 v0, -v0, v11, v9
	v_div_fmas_f32 v0, v0, v7, v11
	v_div_fixup_f32 v2, v0, v2, v6
	v_lshlrev_b32_e32 v6, 16, v1
	v_and_b32_e32 v7, 0xffff0000, v1
	v_mul_f32_e32 v0, 0xbfb8aa3b, v6
	v_mul_f32_e32 v1, 0xbfb8aa3b, v7
	v_exp_f32_e32 v0, v0
	v_exp_f32_e32 v1, v1
	v_pk_mul_f32 v[2:3], v[40:41], v[2:3]
	v_pk_add_f32 v[0:1], v[0:1], 1.0 op_sel_hi:[1,0]
	s_nop 0
	v_div_scale_f32 v9, s[0:1], v1, v1, v7
	v_rcp_f32_e32 v11, v9
	s_nop 0
	v_fma_f32 v12, -v9, v11, 1.0
	v_fmac_f32_e32 v11, v12, v11
	v_div_scale_f32 v12, vcc, v7, v1, v7
	v_mul_f32_e32 v13, v12, v11
	v_fma_f32 v14, -v9, v13, v12
	v_fmac_f32_e32 v13, v14, v11
	v_fma_f32 v9, -v9, v13, v12
	v_div_fmas_f32 v9, v9, v11, v13
	v_div_fixup_f32 v1, v9, v1, v7
	v_div_scale_f32 v7, s[0:1], v0, v0, v6
	v_rcp_f32_e32 v9, v7
	s_nop 0
	v_fma_f32 v11, -v7, v9, 1.0
	v_fmac_f32_e32 v9, v11, v9
	v_div_scale_f32 v11, vcc, v6, v0, v6
	v_mul_f32_e32 v12, v11, v9
	v_fma_f32 v13, -v7, v12, v11
	v_fmac_f32_e32 v12, v13, v9
	v_fma_f32 v7, -v7, v12, v11
	v_div_fmas_f32 v7, v7, v9, v12
	v_div_fixup_f32 v0, v7, v0, v6
	v_lshlrev_b32_e32 v9, 16, v8
	v_and_b32_e32 v8, 0xffff0000, v8
	v_pk_mul_f32 v[6:7], v[42:43], v[0:1]
	v_mul_f32_e32 v0, 0xbfb8aa3b, v9
	v_mul_f32_e32 v1, 0xbfb8aa3b, v8
	v_exp_f32_e32 v0, v0
	v_exp_f32_e32 v1, v1
	s_nop 0
	v_pk_add_f32 v[0:1], v[0:1], 1.0 op_sel_hi:[1,0]
	s_nop 0
	v_div_scale_f32 v11, s[0:1], v1, v1, v8
	v_rcp_f32_e32 v12, v11
	s_nop 0
	v_fma_f32 v13, -v11, v12, 1.0
	v_fmac_f32_e32 v12, v13, v12
	v_div_scale_f32 v13, vcc, v8, v1, v8
	v_mul_f32_e32 v14, v13, v12
	v_fma_f32 v15, -v11, v14, v13
	v_fmac_f32_e32 v14, v15, v12
	v_fma_f32 v11, -v11, v14, v13
	v_div_fmas_f32 v11, v11, v12, v14
	v_div_fixup_f32 v1, v11, v1, v8
	v_div_scale_f32 v8, s[0:1], v0, v0, v9
	v_rcp_f32_e32 v11, v8
	s_nop 0
	v_fma_f32 v12, -v8, v11, 1.0
	v_fmac_f32_e32 v11, v12, v11
	v_div_scale_f32 v12, vcc, v9, v0, v9
	v_mul_f32_e32 v13, v12, v11
	v_fma_f32 v14, -v8, v13, v12
	v_fmac_f32_e32 v13, v14, v11
	v_fma_f32 v8, -v8, v13, v12
	v_div_fmas_f32 v8, v8, v11, v13
	v_div_fixup_f32 v0, v8, v0, v9
	v_lshlrev_b32_e32 v11, 16, v10
	v_and_b32_e32 v10, 0xffff0000, v10
	v_pk_mul_f32 v[8:9], v[44:45], v[0:1]
	v_mul_f32_e32 v0, 0xbfb8aa3b, v11
	v_mul_f32_e32 v1, 0xbfb8aa3b, v10
	v_exp_f32_e32 v0, v0
	v_exp_f32_e32 v1, v1
	s_nop 0
	v_pk_add_f32 v[0:1], v[0:1], 1.0 op_sel_hi:[1,0]
	s_nop 0
	v_div_scale_f32 v12, s[0:1], v1, v1, v10
	v_rcp_f32_e32 v13, v12
	s_nop 0
	v_fma_f32 v14, -v12, v13, 1.0
	v_fmac_f32_e32 v13, v14, v13
	v_div_scale_f32 v14, vcc, v10, v1, v10
	v_mul_f32_e32 v15, v14, v13
	v_fma_f32 v16, -v12, v15, v14
	v_fmac_f32_e32 v15, v16, v13
	v_fma_f32 v12, -v12, v15, v14
	v_div_fmas_f32 v12, v12, v13, v15
	v_div_fixup_f32 v1, v12, v1, v10
	v_div_scale_f32 v10, s[0:1], v0, v0, v11
	v_rcp_f32_e32 v12, v10
	s_nop 0
	v_fma_f32 v13, -v10, v12, 1.0
	v_fmac_f32_e32 v12, v13, v12
	v_div_scale_f32 v13, vcc, v11, v0, v11
	v_mul_f32_e32 v14, v13, v12
	v_fma_f32 v15, -v10, v14, v13
	v_fmac_f32_e32 v14, v15, v12
	v_fma_f32 v10, -v10, v14, v13
	v_div_fmas_f32 v10, v10, v12, v14
	v_div_fixup_f32 v0, v10, v0, v11
	v_pk_mul_f32 v[10:11], v[46:47], v[0:1]
	v_cvt_pk_bf16_f32 v0, v2, v3
	v_cvt_pk_bf16_f32 v1, v6, v7
	v_cvt_pk_bf16_f32 v2, v8, v9
	v_cvt_pk_bf16_f32 v3, v10, v11
	s_nop 0
	v_permlane32_swap_b32_e32 v0, v2
	v_permlane32_swap_b32_e32 v1, v3
	global_store_dwordx4 v[4:5], v[0:3], off offset:96

.LBB0_714:
	v_cmp_lt_i32_e32 vcc, v109, v111
	v_lshlrev_b32_e32 v192, 1, v108
	v_readlane_b32 s76, v254, 37
	v_cndmask_b32_e32 v32, v110, v109, vcc
	v_lshlrev_b32_e32 v32, 2, v32
	ds_bpermute_b32 v32, v32, v34
	v_readlane_b32 s77, v254, 38
	s_waitcnt lgkmcnt(0)
	v_add_f32_e32 v32, v34, v32
	v_div_scale_f32 v33, s[0:1], v32, v32, 1.0
	v_rcp_f32_e32 v34, v33
	v_readlane_b32 s0, v254, 9
	v_readlane_b32 s1, v254, 10
	v_fma_f32 v35, -v33, v34, 1.0
	v_fmac_f32_e32 v34, v35, v34
	v_div_scale_f32 v35, vcc, 1.0, v32, 1.0
	v_mul_f32_e32 v36, v35, v34
	v_fma_f32 v37, -v33, v36, v35
	v_fmac_f32_e32 v36, v37, v34
	v_fma_f32 v33, -v33, v36, v35
	v_div_fmas_f32 v33, v33, v34, v36
	v_readlane_b32 s98, v253, 59
	v_readlane_b32 s99, v253, 60
	s_nop 1
	v_writelane_b32 v76, s98, 40
	v_writelane_b32 v77, s99, 40
	s_mov_b64 s[98:99], exec
	v_cmpx_eq_u32_e64 exec, 40, v234
	s_nop 3
	v_writelane_b32 v255, exec_hi, 41
	global_atomic_add v255, v[76:77], v251, off sc0
	s_mov_b64 exec, s[98:99]
	global_load_dwordx4 v[36:39], v[96:97], off offset:1536
	global_load_dwordx4 v[64:67], v[96:97], off offset:1568
	global_load_dwordx4 v[68:71], v[96:97], off offset:1600
	global_load_dwordx4 v[72:75], v[96:97], off offset:1632
	v_div_fixup_f32 v34, v33, v32, 1.0
	v_lshlrev_b64 v[32:33], 11, v[98:99]
	v_lshl_add_u64 v[32:33], s[0:1], 0, v[32:33]
	s_mov_b64 s[0:1], 0x3e38aa3b
	s_mov_b32 s15, s1
	v_lshl_add_u64 v[32:33], v[32:33], 0, s[14:15]
	v_lshl_add_u64 v[32:33], v[32:33], 0, v[192:193]
	s_waitcnt vmcnt(3)
	v_mov_b32_e32 v35, v38
	s_nop 1
	v_permlane32_swap_b32_e32 v36, v35
	v_lshlrev_b32_e32 v41, 16, v36
	v_and_b32_e32 v36, 0xffff0000, v36
	v_mov_b32_e32 v40, v39
	v_mul_f32_e32 v38, 0xbfb8aa3b, v41
	v_mul_f32_e32 v39, 0xbfb8aa3b, v36
	v_exp_f32_e32 v38, v38
	v_exp_f32_e32 v39, v39
	v_permlane32_swap_b32_e32 v37, v40
	v_pk_mul_f32 v[16:17], v[16:17], v[34:35] op_sel_hi:[1,0]
	v_pk_add_f32 v[38:39], v[38:39], 1.0 op_sel_hi:[1,0]
	v_pk_mul_f32 v[18:19], v[18:19], v[34:35] op_sel_hi:[1,0]
	v_div_scale_f32 v42, s[0:1], v39, v39, v36
	v_rcp_f32_e32 v43, v42
	s_nop 0
	v_fma_f32 v44, -v42, v43, 1.0
	v_fmac_f32_e32 v43, v44, v43
	v_div_scale_f32 v44, vcc, v36, v39, v36
	v_mul_f32_e32 v45, v44, v43
	v_fma_f32 v46, -v42, v45, v44
	v_fmac_f32_e32 v45, v46, v43
	v_fma_f32 v42, -v42, v45, v44
	v_div_fmas_f32 v42, v42, v43, v45
	v_div_fixup_f32 v39, v42, v39, v36
	v_div_scale_f32 v36, s[0:1], v38, v38, v41
	v_rcp_f32_e32 v42, v36
	s_nop 0
	v_fma_f32 v43, -v36, v42, 1.0
	v_fmac_f32_e32 v42, v43, v42
	v_div_scale_f32 v43, vcc, v41, v38, v41
	v_mul_f32_e32 v44, v43, v42
	v_fma_f32 v45, -v36, v44, v43
	v_fmac_f32_e32 v44, v45, v42
	v_fma_f32 v36, -v36, v44, v43
	v_div_fmas_f32 v36, v36, v42, v44
	v_div_fixup_f32 v38, v36, v38, v41
	v_pk_mul_f32 v[16:17], v[16:17], v[38:39]
	v_lshlrev_b32_e32 v38, 16, v37
	v_and_b32_e32 v39, 0xffff0000, v37
	v_mul_f32_e32 v36, 0xbfb8aa3b, v38
	v_mul_f32_e32 v37, 0xbfb8aa3b, v39
	v_exp_f32_e32 v36, v36
	v_exp_f32_e32 v37, v37
	v_cvt_pk_bf16_f32 v16, v16, v17
	v_pk_add_f32 v[36:37], v[36:37], 1.0 op_sel_hi:[1,0]
	s_nop 0
	v_div_scale_f32 v41, s[0:1], v37, v37, v39
	v_rcp_f32_e32 v42, v41
	s_nop 0
	v_fma_f32 v43, -v41, v42, 1.0
	v_fmac_f32_e32 v42, v43, v42
	v_div_scale_f32 v43, vcc, v39, v37, v39
	v_mul_f32_e32 v44, v43, v42
	v_fma_f32 v45, -v41, v44, v43
	v_fmac_f32_e32 v44, v45, v42
	v_fma_f32 v41, -v41, v44, v43
	v_div_fmas_f32 v41, v41, v42, v44
	v_div_fixup_f32 v37, v41, v37, v39
	v_div_scale_f32 v39, s[0:1], v36, v36, v38
	v_rcp_f32_e32 v41, v39
	s_nop 0
	v_fma_f32 v42, -v39, v41, 1.0
	v_fmac_f32_e32 v41, v42, v41
	v_div_scale_f32 v42, vcc, v38, v36, v38
	v_mul_f32_e32 v43, v42, v41
	v_fma_f32 v44, -v39, v43, v42
	v_fmac_f32_e32 v43, v44, v41
	v_fma_f32 v39, -v39, v43, v42
	v_div_fmas_f32 v39, v39, v41, v43
	v_div_fixup_f32 v36, v39, v36, v38
	v_lshlrev_b32_e32 v38, 16, v35
	v_and_b32_e32 v35, 0xffff0000, v35
	v_pk_mul_f32 v[18:19], v[18:19], v[36:37]
	v_mul_f32_e32 v36, 0xbfb8aa3b, v38
	v_mul_f32_e32 v37, 0xbfb8aa3b, v35
	v_exp_f32_e32 v36, v36
	v_exp_f32_e32 v37, v37
	v_pk_mul_f32 v[20:21], v[20:21], v[34:35] op_sel_hi:[1,0]
	v_cvt_pk_bf16_f32 v17, v18, v19
	v_pk_add_f32 v[36:37], v[36:37], 1.0 op_sel_hi:[1,0]
	s_nop 0
	v_div_scale_f32 v39, s[0:1], v37, v37, v35
	v_rcp_f32_e32 v41, v39
	s_nop 0
	v_fma_f32 v42, -v39, v41, 1.0
	v_fmac_f32_e32 v41, v42, v41
	v_div_scale_f32 v42, vcc, v35, v37, v35
	v_mul_f32_e32 v43, v42, v41
	v_fma_f32 v44, -v39, v43, v42
	v_fmac_f32_e32 v43, v44, v41
	v_fma_f32 v39, -v39, v43, v42
	v_div_fmas_f32 v39, v39, v41, v43
	v_div_fixup_f32 v37, v39, v37, v35
	v_div_scale_f32 v35, s[0:1], v36, v36, v38
	v_rcp_f32_e32 v39, v35
	s_nop 0
	v_fma_f32 v41, -v35, v39, 1.0
	v_fmac_f32_e32 v39, v41, v39
	v_div_scale_f32 v41, vcc, v38, v36, v38
	v_mul_f32_e32 v42, v41, v39
	v_fma_f32 v43, -v35, v42, v41
	v_fmac_f32_e32 v42, v43, v39
	v_fma_f32 v35, -v35, v42, v41
	v_div_fmas_f32 v35, v35, v39, v42
	v_div_fixup_f32 v36, v35, v36, v38
	v_lshlrev_b32_e32 v35, 16, v40
	v_and_b32_e32 v38, 0xffff0000, v40
	v_pk_mul_f32 v[20:21], v[20:21], v[36:37]
	v_mul_f32_e32 v36, 0xbfb8aa3b, v35
	v_mul_f32_e32 v37, 0xbfb8aa3b, v38
	v_exp_f32_e32 v36, v36
	v_exp_f32_e32 v37, v37
	v_pk_mul_f32 v[22:23], v[22:23], v[34:35] op_sel_hi:[1,0]
	v_cvt_pk_bf16_f32 v18, v20, v21
	s_nop 1
	v_permlane32_swap_b32_e32 v16, v18
	v_pk_add_f32 v[36:37], v[36:37], 1.0 op_sel_hi:[1,0]
	s_nop 0
	v_div_scale_f32 v39, s[0:1], v37, v37, v38
	v_rcp_f32_e32 v40, v39
	s_nop 0
	v_fma_f32 v41, -v39, v40, 1.0
	v_fmac_f32_e32 v40, v41, v40
	v_div_scale_f32 v41, vcc, v38, v37, v38
	v_mul_f32_e32 v42, v41, v40
	v_fma_f32 v43, -v39, v42, v41
	v_fmac_f32_e32 v42, v43, v40
	v_fma_f32 v39, -v39, v42, v41
	v_div_fmas_f32 v39, v39, v40, v42
	v_div_fixup_f32 v37, v39, v37, v38
	v_div_scale_f32 v38, s[0:1], v36, v36, v35
	v_rcp_f32_e32 v39, v38
	s_nop 0
	v_fma_f32 v40, -v38, v39, 1.0
	v_fmac_f32_e32 v39, v40, v39
	v_div_scale_f32 v40, vcc, v35, v36, v35
	v_mul_f32_e32 v41, v40, v39
	v_fma_f32 v42, -v38, v41, v40
	v_fmac_f32_e32 v41, v42, v39
	v_fma_f32 v38, -v38, v41, v40
	v_div_fmas_f32 v38, v38, v39, v41
	v_div_fixup_f32 v36, v38, v36, v35
	v_pk_mul_f32 v[22:23], v[22:23], v[36:37]
	s_nop 0
	v_cvt_pk_bf16_f32 v19, v22, v23
	s_nop 1
	v_permlane32_swap_b32_e32 v17, v19
	global_store_dwordx4 v[32:33], v[16:19], off
	s_waitcnt vmcnt(3)
	v_mov_b32_e32 v22, v66
	s_nop 1
	v_mov_b32_e32 v16, v64
	s_nop 1
	v_permlane32_swap_b32_e32 v16, v22
	v_lshlrev_b32_e32 v23, 16, v16
	v_and_b32_e32 v16, 0xffff0000, v16
	v_mul_f32_e32 v20, 0xbfb8aa3b, v23
	v_mul_f32_e32 v21, 0xbfb8aa3b, v16
	v_exp_f32_e32 v20, v20
	v_exp_f32_e32 v21, v21
	v_mov_b32_e32 v35, v67
	s_nop 1
	v_mov_b32_e32 v17, v65
	s_nop 1
	v_permlane32_swap_b32_e32 v17, v35
	v_pk_add_f32 v[20:21], v[20:21], 1.0 op_sel_hi:[1,0]
	v_pk_mul_f32 v[18:19], v[24:25], v[34:35] op_sel_hi:[1,0]
	v_div_scale_f32 v24, s[0:1], v21, v21, v16
	v_rcp_f32_e32 v25, v24
	s_nop 0
	v_fma_f32 v36, -v24, v25, 1.0
	v_fmac_f32_e32 v25, v36, v25
	v_div_scale_f32 v36, vcc, v16, v21, v16
	v_mul_f32_e32 v37, v36, v25
	v_fma_f32 v38, -v24, v37, v36
	v_fmac_f32_e32 v37, v38, v25
	v_fma_f32 v24, -v24, v37, v36
	v_div_fmas_f32 v24, v24, v25, v37
	v_div_fixup_f32 v21, v24, v21, v16
	v_div_scale_f32 v16, s[0:1], v20, v20, v23
	v_rcp_f32_e32 v24, v16
	s_nop 0
	v_fma_f32 v25, -v16, v24, 1.0
	v_fmac_f32_e32 v24, v25, v24
	v_div_scale_f32 v25, vcc, v23, v20, v23
	v_mul_f32_e32 v36, v25, v24
	v_fma_f32 v37, -v16, v36, v25
	v_fmac_f32_e32 v36, v37, v24
	v_fma_f32 v16, -v16, v36, v25
	v_div_fmas_f32 v16, v16, v24, v36
	v_div_fixup_f32 v20, v16, v20, v23
	v_lshlrev_b32_e32 v23, 16, v17
	v_and_b32_e32 v24, 0xffff0000, v17
	v_pk_mul_f32 v[18:19], v[18:19], v[20:21]
	v_mul_f32_e32 v20, 0xbfb8aa3b, v23
	v_mul_f32_e32 v21, 0xbfb8aa3b, v24
	v_exp_f32_e32 v20, v20
	v_exp_f32_e32 v21, v21
	v_pk_mul_f32 v[16:17], v[26:27], v[34:35] op_sel_hi:[1,0]
	v_pk_add_f32 v[20:21], v[20:21], 1.0 op_sel_hi:[1,0]
	s_nop 0
	v_div_scale_f32 v25, s[0:1], v21, v21, v24
	v_rcp_f32_e32 v26, v25
	s_nop 0
	v_fma_f32 v27, -v25, v26, 1.0
	v_fmac_f32_e32 v26, v27, v26
	v_div_scale_f32 v27, vcc, v24, v21, v24
	v_mul_f32_e32 v36, v27, v26
	v_fma_f32 v37, -v25, v36, v27
	v_fmac_f32_e32 v36, v37, v26
	v_fma_f32 v25, -v25, v36, v27
	v_div_fmas_f32 v25, v25, v26, v36
	v_div_fixup_f32 v21, v25, v21, v24
	v_div_scale_f32 v24, s[0:1], v20, v20, v23
	v_rcp_f32_e32 v25, v24
	s_nop 0
	v_fma_f32 v26, -v24, v25, 1.0
	v_fmac_f32_e32 v25, v26, v25
	v_div_scale_f32 v26, vcc, v23, v20, v23
	v_mul_f32_e32 v27, v26, v25
	v_fma_f32 v36, -v24, v27, v26
	v_fmac_f32_e32 v27, v36, v25
	v_fma_f32 v24, -v24, v27, v26
	v_div_fmas_f32 v24, v24, v25, v27
	v_div_fixup_f32 v20, v24, v20, v23
	v_lshlrev_b32_e32 v24, 16, v22
	v_and_b32_e32 v25, 0xffff0000, v22
	v_mul_f32_e32 v22, 0xbfb8aa3b, v24
	v_mul_f32_e32 v23, 0xbfb8aa3b, v25
	v_exp_f32_e32 v22, v22
	v_exp_f32_e32 v23, v23
	v_pk_mul_f32 v[20:21], v[16:17], v[20:21]
	v_pk_mul_f32 v[16:17], v[28:29], v[34:35] op_sel_hi:[1,0]
	v_pk_add_f32 v[22:23], v[22:23], 1.0 op_sel_hi:[1,0]
	s_nop 0
	v_div_scale_f32 v26, s[0:1], v23, v23, v25
	v_rcp_f32_e32 v27, v26
	s_nop 0
	v_fma_f32 v28, -v26, v27, 1.0
	v_fmac_f32_e32 v27, v28, v27
	v_div_scale_f32 v28, vcc, v25, v23, v25
	v_mul_f32_e32 v29, v28, v27
	v_fma_f32 v36, -v26, v29, v28
	v_fmac_f32_e32 v29, v36, v27
	v_fma_f32 v26, -v26, v29, v28
	v_div_fmas_f32 v26, v26, v27, v29
	v_div_fixup_f32 v23, v26, v23, v25
	v_div_scale_f32 v25, s[0:1], v22, v22, v24
	v_rcp_f32_e32 v26, v25
	s_nop 0
	v_fma_f32 v27, -v25, v26, 1.0
	v_fmac_f32_e32 v26, v27, v26
	v_div_scale_f32 v27, vcc, v24, v22, v24
	v_mul_f32_e32 v28, v27, v26
	v_fma_f32 v29, -v25, v28, v27
	v_fmac_f32_e32 v28, v29, v26
	v_fma_f32 v25, -v25, v28, v27
	v_div_fmas_f32 v25, v25, v26, v28
	v_lshlrev_b32_e32 v26, 16, v35
	v_and_b32_e32 v27, 0xffff0000, v35
	v_div_fixup_f32 v22, v25, v22, v24
	v_mul_f32_e32 v24, 0xbfb8aa3b, v26
	v_mul_f32_e32 v25, 0xbfb8aa3b, v27
	v_exp_f32_e32 v24, v24
	v_exp_f32_e32 v25, v25
	v_pk_mul_f32 v[22:23], v[16:17], v[22:23]
	v_pk_mul_f32 v[16:17], v[30:31], v[34:35] op_sel_hi:[1,0]
	v_pk_add_f32 v[24:25], v[24:25], 1.0 op_sel_hi:[1,0]
	s_nop 0
	v_div_scale_f32 v28, s[0:1], v25, v25, v27
	v_rcp_f32_e32 v29, v28
	s_nop 0
	v_fma_f32 v30, -v28, v29, 1.0
	v_fmac_f32_e32 v29, v30, v29
	v_div_scale_f32 v30, vcc, v27, v25, v27
	v_mul_f32_e32 v31, v30, v29
	v_fma_f32 v35, -v28, v31, v30
	v_fmac_f32_e32 v31, v35, v29
	v_fma_f32 v28, -v28, v31, v30
	v_div_fmas_f32 v28, v28, v29, v31
	v_div_fixup_f32 v25, v28, v25, v27
	v_div_scale_f32 v27, s[0:1], v24, v24, v26
	v_rcp_f32_e32 v28, v27
	v_pk_mul_f32 v[0:1], v[0:1], v[34:35] op_sel_hi:[1,0]
	v_pk_mul_f32 v[2:3], v[2:3], v[34:35] op_sel_hi:[1,0]
	v_pk_mul_f32 v[4:5], v[4:5], v[34:35] op_sel_hi:[1,0]
	v_fma_f32 v29, -v27, v28, 1.0
	v_fmac_f32_e32 v28, v29, v28
	v_div_scale_f32 v29, vcc, v26, v24, v26
	v_mul_f32_e32 v30, v29, v28
	v_fma_f32 v31, -v27, v30, v29
	v_fmac_f32_e32 v30, v31, v28
	v_fma_f32 v27, -v27, v30, v29
	v_div_fmas_f32 v27, v27, v28, v30
	v_div_fixup_f32 v24, v27, v24, v26
	v_pk_mul_f32 v[24:25], v[16:17], v[24:25]
	v_cvt_pk_bf16_f32 v16, v18, v19
	v_cvt_pk_bf16_f32 v17, v20, v21
	v_cvt_pk_bf16_f32 v18, v22, v23
	v_cvt_pk_bf16_f32 v19, v24, v25
	s_nop 0
	v_permlane32_swap_b32_e32 v16, v18
	v_permlane32_swap_b32_e32 v17, v19
	global_store_dwordx4 v[32:33], v[16:19], off offset:32
	v_pk_mul_f32 v[6:7], v[6:7], v[34:35] op_sel_hi:[1,0]
	s_waitcnt vmcnt(3)
	v_mov_b32_e32 v20, v70
	s_nop 1
	v_mov_b32_e32 v16, v68
	s_nop 1
	v_permlane32_swap_b32_e32 v16, v20
	v_lshlrev_b32_e32 v22, 16, v16
	v_and_b32_e32 v16, 0xffff0000, v16
	v_mov_b32_e32 v21, v71
	v_mul_f32_e32 v18, 0xbfb8aa3b, v22
	v_mul_f32_e32 v19, 0xbfb8aa3b, v16
	v_exp_f32_e32 v18, v18
	v_exp_f32_e32 v19, v19
	v_mov_b32_e32 v17, v69
	s_nop 1
	v_permlane32_swap_b32_e32 v17, v21
	v_pk_add_f32 v[18:19], v[18:19], 1.0 op_sel_hi:[1,0]
	s_nop 0
	v_div_scale_f32 v23, s[0:1], v19, v19, v16
	v_rcp_f32_e32 v24, v23
	s_nop 0
	v_fma_f32 v25, -v23, v24, 1.0
	v_fmac_f32_e32 v24, v25, v24
	v_div_scale_f32 v25, vcc, v16, v19, v16
	v_mul_f32_e32 v26, v25, v24
	v_fma_f32 v27, -v23, v26, v25
	v_fmac_f32_e32 v26, v27, v24
	v_fma_f32 v23, -v23, v26, v25
	v_div_fmas_f32 v23, v23, v24, v26
	v_div_fixup_f32 v19, v23, v19, v16
	v_div_scale_f32 v16, s[0:1], v18, v18, v22
	v_rcp_f32_e32 v23, v16
	s_nop 0
	v_fma_f32 v24, -v16, v23, 1.0
	v_fmac_f32_e32 v23, v24, v23
	v_div_scale_f32 v24, vcc, v22, v18, v22
	v_mul_f32_e32 v25, v24, v23
	v_fma_f32 v26, -v16, v25, v24
	v_fmac_f32_e32 v25, v26, v23
	v_fma_f32 v16, -v16, v25, v24
	v_div_fmas_f32 v16, v16, v23, v25
	v_div_fixup_f32 v18, v16, v18, v22
	v_pk_mul_f32 v[0:1], v[0:1], v[18:19]
	v_lshlrev_b32_e32 v18, 16, v17
	v_and_b32_e32 v19, 0xffff0000, v17
	v_mul_f32_e32 v16, 0xbfb8aa3b, v18
	v_mul_f32_e32 v17, 0xbfb8aa3b, v19
	v_exp_f32_e32 v16, v16
	v_exp_f32_e32 v17, v17
	v_cvt_pk_bf16_f32 v0, v0, v1
	v_pk_add_f32 v[16:17], v[16:17], 1.0 op_sel_hi:[1,0]
	s_nop 0
	v_div_scale_f32 v22, s[0:1], v17, v17, v19
	v_rcp_f32_e32 v23, v22
	s_nop 0
	v_fma_f32 v24, -v22, v23, 1.0
	v_fmac_f32_e32 v23, v24, v23
	v_div_scale_f32 v24, vcc, v19, v17, v19
	v_mul_f32_e32 v25, v24, v23
	v_fma_f32 v26, -v22, v25, v24
	v_fmac_f32_e32 v25, v26, v23
	v_fma_f32 v22, -v22, v25, v24
	v_div_fmas_f32 v22, v22, v23, v25
	v_div_fixup_f32 v17, v22, v17, v19
	v_div_scale_f32 v19, s[0:1], v16, v16, v18
	v_rcp_f32_e32 v22, v19
	s_nop 0
	v_fma_f32 v23, -v19, v22, 1.0
	v_fmac_f32_e32 v22, v23, v22
	v_div_scale_f32 v23, vcc, v18, v16, v18
	v_mul_f32_e32 v24, v23, v22
	v_fma_f32 v25, -v19, v24, v23
	v_fmac_f32_e32 v24, v25, v22
	v_fma_f32 v19, -v19, v24, v23
	v_div_fmas_f32 v19, v19, v22, v24
	v_div_fixup_f32 v16, v19, v16, v18
	v_lshlrev_b32_e32 v18, 16, v20
	v_and_b32_e32 v19, 0xffff0000, v20
	v_pk_mul_f32 v[2:3], v[2:3], v[16:17]
	v_mul_f32_e32 v16, 0xbfb8aa3b, v18
	v_mul_f32_e32 v17, 0xbfb8aa3b, v19
	v_exp_f32_e32 v16, v16
	v_exp_f32_e32 v17, v17
	v_cvt_pk_bf16_f32 v1, v2, v3
	v_pk_add_f32 v[16:17], v[16:17], 1.0 op_sel_hi:[1,0]
	s_nop 0
	v_div_scale_f32 v20, s[0:1], v17, v17, v19
	v_rcp_f32_e32 v22, v20
	s_nop 0
	v_fma_f32 v23, -v20, v22, 1.0
	v_fmac_f32_e32 v22, v23, v22
	v_div_scale_f32 v23, vcc, v19, v17, v19
	v_mul_f32_e32 v24, v23, v22
	v_fma_f32 v25, -v20, v24, v23
	v_fmac_f32_e32 v24, v25, v22
	v_fma_f32 v20, -v20, v24, v23
	v_div_fmas_f32 v20, v20, v22, v24
	v_div_fixup_f32 v17, v20, v17, v19
	v_div_scale_f32 v19, s[0:1], v16, v16, v18
	v_rcp_f32_e32 v20, v19
	s_nop 0
	v_fma_f32 v22, -v19, v20, 1.0
	v_fmac_f32_e32 v20, v22, v20
	v_div_scale_f32 v22, vcc, v18, v16, v18
	v_mul_f32_e32 v23, v22, v20
	v_fma_f32 v24, -v19, v23, v22
	v_fmac_f32_e32 v23, v24, v20
	v_fma_f32 v19, -v19, v23, v22
	v_div_fmas_f32 v19, v19, v20, v23
	v_div_fixup_f32 v16, v19, v16, v18
	v_lshlrev_b32_e32 v18, 16, v21
	v_and_b32_e32 v19, 0xffff0000, v21
	v_pk_mul_f32 v[4:5], v[4:5], v[16:17]
	v_mul_f32_e32 v16, 0xbfb8aa3b, v18
	v_mul_f32_e32 v17, 0xbfb8aa3b, v19
	v_exp_f32_e32 v16, v16
	v_exp_f32_e32 v17, v17
	v_cvt_pk_bf16_f32 v2, v4, v5
	s_nop 1
	v_permlane32_swap_b32_e32 v0, v2
	v_pk_add_f32 v[16:17], v[16:17], 1.0 op_sel_hi:[1,0]
	s_nop 0
	v_div_scale_f32 v20, s[0:1], v17, v17, v19
	v_rcp_f32_e32 v21, v20
	s_nop 0
	v_fma_f32 v22, -v20, v21, 1.0
	v_fmac_f32_e32 v21, v22, v21
	v_div_scale_f32 v22, vcc, v19, v17, v19
	v_mul_f32_e32 v23, v22, v21
	v_fma_f32 v24, -v20, v23, v22
	v_fmac_f32_e32 v23, v24, v21
	v_fma_f32 v20, -v20, v23, v22
	v_div_fmas_f32 v20, v20, v21, v23
	v_div_fixup_f32 v17, v20, v17, v19
	v_div_scale_f32 v19, s[0:1], v16, v16, v18
	v_rcp_f32_e32 v20, v19
	s_nop 0
	v_fma_f32 v21, -v19, v20, 1.0
	v_fmac_f32_e32 v20, v21, v20
	v_div_scale_f32 v21, vcc, v18, v16, v18
	v_mul_f32_e32 v22, v21, v20
	v_fma_f32 v23, -v19, v22, v21
	v_fmac_f32_e32 v22, v23, v20
	v_fma_f32 v19, -v19, v22, v21
	v_div_fmas_f32 v19, v19, v20, v22
	v_div_fixup_f32 v16, v19, v16, v18
	v_pk_mul_f32 v[6:7], v[6:7], v[16:17]
	s_nop 0
	v_cvt_pk_bf16_f32 v3, v6, v7
	s_nop 1
	v_permlane32_swap_b32_e32 v1, v3
	global_store_dwordx4 v[32:33], v[0:3], off offset:64
	s_waitcnt vmcnt(3)
	v_mov_b32_e32 v6, v74
	s_nop 1
	v_mov_b32_e32 v0, v72
	s_nop 1
	v_permlane32_swap_b32_e32 v0, v6
	v_lshlrev_b32_e32 v7, 16, v0
	v_and_b32_e32 v0, 0xffff0000, v0
	v_mul_f32_e32 v4, 0xbfb8aa3b, v7
	v_mul_f32_e32 v5, 0xbfb8aa3b, v0
	v_exp_f32_e32 v4, v4
	v_exp_f32_e32 v5, v5
	v_mov_b32_e32 v16, v75
	v_pk_mul_f32 v[2:3], v[8:9], v[34:35] op_sel_hi:[1,0]
	s_nop 0
	v_mov_b32_e32 v1, v73
	s_nop 1
	v_permlane32_swap_b32_e32 v1, v16
	v_pk_add_f32 v[4:5], v[4:5], 1.0 op_sel_hi:[1,0]
	s_nop 0
	v_div_scale_f32 v8, s[0:1], v5, v5, v0
	v_rcp_f32_e32 v9, v8
	s_nop 0
	v_fma_f32 v17, -v8, v9, 1.0
	v_fmac_f32_e32 v9, v17, v9
	v_div_scale_f32 v17, vcc, v0, v5, v0
	v_mul_f32_e32 v18, v17, v9
	v_fma_f32 v19, -v8, v18, v17
	v_fmac_f32_e32 v18, v19, v9
	v_fma_f32 v8, -v8, v18, v17
	v_div_fmas_f32 v8, v8, v9, v18
	v_div_fixup_f32 v5, v8, v5, v0
	v_div_scale_f32 v0, s[0:1], v4, v4, v7
	v_rcp_f32_e32 v8, v0
	s_nop 0
	v_fma_f32 v9, -v0, v8, 1.0
	v_fmac_f32_e32 v8, v9, v8
	v_div_scale_f32 v9, vcc, v7, v4, v7
	v_mul_f32_e32 v17, v9, v8
	v_fma_f32 v18, -v0, v17, v9
	v_fmac_f32_e32 v17, v18, v8
	v_fma_f32 v0, -v0, v17, v9
	v_div_fmas_f32 v0, v0, v8, v17
	v_div_fixup_f32 v4, v0, v4, v7
	v_lshlrev_b32_e32 v7, 16, v1
	v_and_b32_e32 v8, 0xffff0000, v1
	v_pk_mul_f32 v[2:3], v[2:3], v[4:5]
	v_mul_f32_e32 v4, 0xbfb8aa3b, v7
	v_mul_f32_e32 v5, 0xbfb8aa3b, v8
	v_exp_f32_e32 v4, v4
	v_exp_f32_e32 v5, v5
	v_pk_mul_f32 v[0:1], v[10:11], v[34:35] op_sel_hi:[1,0]
	v_pk_add_f32 v[4:5], v[4:5], 1.0 op_sel_hi:[1,0]
	s_nop 0
	v_div_scale_f32 v9, s[0:1], v5, v5, v8
	v_rcp_f32_e32 v10, v9
	s_nop 0
	v_fma_f32 v11, -v9, v10, 1.0
	v_fmac_f32_e32 v10, v11, v10
	v_div_scale_f32 v11, vcc, v8, v5, v8
	v_mul_f32_e32 v17, v11, v10
	v_fma_f32 v18, -v9, v17, v11
	v_fmac_f32_e32 v17, v18, v10
	v_fma_f32 v9, -v9, v17, v11
	v_div_fmas_f32 v9, v9, v10, v17
	v_div_fixup_f32 v5, v9, v5, v8
	v_div_scale_f32 v8, s[0:1], v4, v4, v7
	v_rcp_f32_e32 v9, v8
	s_nop 0
	v_fma_f32 v10, -v8, v9, 1.0
	v_fmac_f32_e32 v9, v10, v9
	v_div_scale_f32 v10, vcc, v7, v4, v7
	v_mul_f32_e32 v11, v10, v9
	v_fma_f32 v17, -v8, v11, v10
	v_fmac_f32_e32 v11, v17, v9
	v_fma_f32 v8, -v8, v11, v10
	v_div_fmas_f32 v8, v8, v9, v11
	v_div_fixup_f32 v4, v8, v4, v7
	v_lshlrev_b32_e32 v8, 16, v6
	v_and_b32_e32 v9, 0xffff0000, v6
	v_mul_f32_e32 v6, 0xbfb8aa3b, v8
	v_mul_f32_e32 v7, 0xbfb8aa3b, v9
	v_exp_f32_e32 v6, v6
	v_exp_f32_e32 v7, v7
	v_pk_mul_f32 v[4:5], v[0:1], v[4:5]
	v_pk_mul_f32 v[0:1], v[12:13], v[34:35] op_sel_hi:[1,0]
	v_pk_add_f32 v[6:7], v[6:7], 1.0 op_sel_hi:[1,0]
	s_nop 0
	v_div_scale_f32 v10, s[0:1], v7, v7, v9
	v_rcp_f32_e32 v11, v10
	s_nop 0
	v_fma_f32 v12, -v10, v11, 1.0
	v_fmac_f32_e32 v11, v12, v11
	v_div_scale_f32 v12, vcc, v9, v7, v9
	v_mul_f32_e32 v13, v12, v11
	v_fma_f32 v17, -v10, v13, v12
	v_fmac_f32_e32 v13, v17, v11
	v_fma_f32 v10, -v10, v13, v12
	v_div_fmas_f32 v10, v10, v11, v13
	v_div_fixup_f32 v7, v10, v7, v9
	v_div_scale_f32 v9, s[0:1], v6, v6, v8
	v_rcp_f32_e32 v10, v9
	s_nop 0
	v_fma_f32 v11, -v9, v10, 1.0
	v_fmac_f32_e32 v10, v11, v10
	v_div_scale_f32 v11, vcc, v8, v6, v8
	v_mul_f32_e32 v12, v11, v10
	v_fma_f32 v13, -v9, v12, v11
	v_fmac_f32_e32 v12, v13, v10
	v_fma_f32 v9, -v9, v12, v11
	v_div_fmas_f32 v9, v9, v10, v12
	v_lshlrev_b32_e32 v10, 16, v16
	v_and_b32_e32 v11, 0xffff0000, v16
	v_div_fixup_f32 v6, v9, v6, v8
	v_mul_f32_e32 v8, 0xbfb8aa3b, v10
	v_mul_f32_e32 v9, 0xbfb8aa3b, v11
	v_exp_f32_e32 v8, v8
	v_exp_f32_e32 v9, v9
	v_pk_mul_f32 v[6:7], v[0:1], v[6:7]
	v_pk_mul_f32 v[0:1], v[14:15], v[34:35] op_sel_hi:[1,0]
	v_pk_add_f32 v[8:9], v[8:9], 1.0 op_sel_hi:[1,0]
	s_nop 0
	v_div_scale_f32 v12, s[0:1], v9, v9, v11
	v_rcp_f32_e32 v13, v12
	s_nop 0
	v_fma_f32 v14, -v12, v13, 1.0
	v_fmac_f32_e32 v13, v14, v13
	v_div_scale_f32 v14, vcc, v11, v9, v11
	v_mul_f32_e32 v15, v14, v13
	v_fma_f32 v16, -v12, v15, v14
	v_fmac_f32_e32 v15, v16, v13
	v_fma_f32 v12, -v12, v15, v14
	v_div_fmas_f32 v12, v12, v13, v15
	v_div_fixup_f32 v9, v12, v9, v11
	v_div_scale_f32 v11, s[0:1], v8, v8, v10
	v_rcp_f32_e32 v12, v11
	s_nop 0
	v_fma_f32 v13, -v11, v12, 1.0
	v_fmac_f32_e32 v12, v13, v12
	v_div_scale_f32 v13, vcc, v10, v8, v10
	v_mul_f32_e32 v14, v13, v12
	v_fma_f32 v15, -v11, v14, v13
	v_fmac_f32_e32 v14, v15, v12
	v_fma_f32 v11, -v11, v14, v13
	v_div_fmas_f32 v11, v11, v12, v14
	v_div_fixup_f32 v8, v11, v8, v10
	v_pk_mul_f32 v[8:9], v[0:1], v[8:9]
	v_cvt_pk_bf16_f32 v0, v2, v3
	v_cvt_pk_bf16_f32 v1, v4, v5
	v_cvt_pk_bf16_f32 v2, v6, v7
	v_cvt_pk_bf16_f32 v3, v8, v9
	s_nop 0
	v_permlane32_swap_b32_e32 v0, v2
	v_permlane32_swap_b32_e32 v1, v3
	global_store_dwordx4 v[32:33], v[0:3], off offset:96
